# merge phase: three gated projection GEMMs fused into one K=2048 GEMM on the RESID instance, accumulator rescaled by gate ratios at K-tile 16/24, weights converted into one combined matrix
# speedup vs baseline: 1.0186x; 1.0159x over previous
; __global__ void __launch_bounds__(NTHR, 2) fwd(Args a) {
;     ...
;         bf16_t* XB = (bf16_t*)(ws + WS_XB); bf16_t* MRG = (bf16_t*)(ws + WS_MRG);
;         bf16_t* PROJ = (bf16_t*)(ws + WS_PROJ); bf16_t* YCAT = (bf16_t*)(ws + WS_YCAT); bf16_t* YS = (bf16_t*)(ws + WS_YS); float* SST = (float*)(ws + WS_SST);
;         bf16_t* ACT = (bf16_t*)(ws + WS_ACT); float* RAW = (float*)(ws + WS_RAW);
;         {
;             const int l = ph / PPL, sp = ph % PPL;
;             const unsigned char* wl = ws + WS_W;
;             float* SS = (float*)(ws + WS_SS);
;             float* COEF = (float*)(ws + WS_COEF);
;             if (sp == 0) { ssm_coef_phase(ap, l, COEF, gw, lane); convert_phase(ap, l, lds, gw, NGW, wave, lane); if (l == 0) xb_phase(ap->in[0], XB, SS, gw, NGW, lane); }
;             else if (sp == 1) { pg8::Epi<pg8::EP_INPROJ> E{PROJ, INW, ap->in[3] + l * 6144, nullptr, 0, nullptr, nullptr, SS + (size_t)(2 * l) * M, nullptr, nullptr}; run_gemm<pg8::EP_INPROJ>(lds, XB, D, (const bf16_t*)(wl + O_WIN), M, INW, D, E, wave); }
;             else if (sp == 2) {
;                 for (int u = blockIdx.x; u < 256; u += G) attn_unit(lds, PROJ, YCAT, ap->in[4] + l * 128, ap->in[5] + l * 128, ap->in[6] + l * 8, u, tid, wave, lane);
;                 for (int u = blockIdx.x; u < 512; u += G) sg_unit(lds, PROJ, YCAT, ap->in[7] + l * 512, ap->in[8] + l * 512, ap->in[9] + (size_t)l * 4 * 128 * 128, ap->in[10] + l * 512, u, tid, wave, lane);
;                 for (int u = gw; u < 4096; u += NGW) ssm_unit<false>(ap, COEF, l, PROJ, SST, YS, lds + wave * 4352, u, lane);
;             }
;             else if (sp == 3) { for (int u = gw; u < 4096; u += NGW) ssm_pass3h(ap, COEF, l, PROJ, SST, YS, lds + wave * 8448, u, lane); }
;             else if (sp == 4) { pg8::Epi<pg8::EP_GLU> E{YCAT + 1536, D, ap->in[20] + l * 512, YS, 512, nullptr}; run_gemm<pg8::EP_GLU>(lds, YS, 512, (const bf16_t*)(wl + O_WGLU), M, 512, 512, E, wave); }
;             else if (sp == 5) {
;                 { pg8::Epi<pg8::EP_MERGE0> E{MRG, D, nullptr, PROJ + 3072, INW, nullptr}; run_gemm<pg8::EP_MERGE0>(lds, YCAT, D, (const bf16_t*)(wl + O_WA), M, D, 1024, E, wave); }
; #pragma unroll 1
;                 for (int j = 1; j < 3; ++j) { pg8::Epi<pg8::EP_MERGE1> E{MRG, D, nullptr, PROJ + 3072 + j * D, INW, nullptr};
.LBB0_10:
	s_mov_b32 s100, 0
	v_readlane_b32 s82, v252, 2
	v_readlane_b32 s83, v252, 3
	v_mov_b32_e32 v167, v195
	s_waitcnt lgkmcnt(0)
	s_load_dwordx2 s[28:29], s[82:83], 0xf8
	v_readlane_b32 s4, v252, 0
	s_mul_hi_i32 s2, s4, 0x66666667
	s_mov_b64 s[0:1], -1
	s_mov_b64 s[12:13], 0
	s_waitcnt lgkmcnt(0)
	s_add_u32 s6, s28, 0x7700000
	s_addc_u32 s7, s29, 0
	s_add_u32 s68, s28, 0xf700000
	v_writelane_b32 v253, s6, 60
	s_addc_u32 s69, s29, 0
	v_readlane_b32 s5, v252, 1
	v_writelane_b32 v253, s7, 61
	s_add_u32 s6, s28, 0x21700000
	s_addc_u32 s7, s29, 0
	s_add_u32 s14, s28, 0x25700000
	s_addc_u32 s15, s29, 0
	s_lshr_b32 s3, s2, 31
	s_ashr_i32 s2, s2, 2
	s_add_i32 s86, s2, s3
	s_mul_i32 s2, s86, 10
	s_sub_i32 s77, s4, s2
	s_add_u32 s2, s28, 0x26900000
	v_writelane_b32 v254, s2, 0
	s_addc_u32 s2, s29, 0
	v_writelane_b32 v254, s2, 1
	v_writelane_b32 v253, s6, 62
	s_mov_b64 s[2:3], 0
	v_writelane_b32 v254, s2, 2
	v_writelane_b32 v253, s7, 63
	s_cmp_lt_i32 s77, 4
	v_writelane_b32 v254, s3, 3
	s_mov_b64 s[2:3], 0
	v_writelane_b32 v254, s2, 4
	s_nop 1
	v_writelane_b32 v254, s3, 5
	s_mov_b32 s2, s26
	v_writelane_b32 v254, s2, 6
	s_nop 1
	v_writelane_b32 v254, s3, 7
	v_writelane_b32 v254, s28, 8
	s_nop 1
	v_writelane_b32 v254, s29, 9
	v_writelane_b32 v254, s68, 10
	s_nop 1
	v_writelane_b32 v254, s69, 11
	s_cbranch_scc1 .LBB0_136
	s_add_u32 s88, s28, 0xb700000
	s_addc_u32 s89, s29, 0
	s_mov_b64 s[2:3], 0
	v_writelane_b32 v254, s2, 2
	s_cmp_gt_i32 s77, 5
	s_nop 0
	v_writelane_b32 v254, s3, 3
	s_cbranch_scc0 .LBB0_17
	s_mov_b64 s[2:3], 0
	v_writelane_b32 v254, s2, 4
	s_cmp_gt_i32 s77, 6
	s_nop 0
	v_writelane_b32 v254, s3, 5
	s_cbranch_scc0 .LBB0_67
	s_add_u32 s16, s28, 0x1a700000
	s_addc_u32 s17, s29, 0
	s_cmp_gt_i32 s77, 7
	s_cbranch_scc0 .LBB0_31
	s_cmp_eq_u32 s77, 8
	s_cbranch_scc0 .LBB0_33
	v_readlane_b32 s0, v252, 8
	s_movk_i32 s38, 0x2c00
	s_waitcnt vmcnt(7)
	v_add_u32_e32 v36, s0, v167
	s_mov_b32 s0, 0xb0000
	v_cmp_gt_i32_e32 vcc, s0, v36
	s_and_saveexec_b64 s[2:3], vcc
	s_cbranch_execz .LBB0_32
	s_load_dwordx4 s[4:7], s[82:83], 0xd8
	s_mul_i32 s1, s86, 0x21000
	s_mul_hi_i32 s0, s86, 0x21000
	s_mul_i32 s9, s86, 0xb000
	s_mul_hi_i32 s8, s86, 0xb000
	s_waitcnt lgkmcnt(0)
	s_add_u32 s4, s4, s1
	s_addc_u32 s5, s5, s0
	s_add_u32 s6, s6, s9
	s_addc_u32 s7, s7, s8
	s_add_u32 s8, s4, 0xb000
	s_addc_u32 s9, s5, 0
	s_add_u32 s10, s4, 0x16000
	s_addc_u32 s11, s5, 0
	s_add_u32 s18, s6, 0x5800
	s_addc_u32 s19, s7, 0
	s_add_u32 s20, s4, 0x5800
	s_addc_u32 s21, s5, 0
	s_add_u32 s22, s4, 0x10800
	s_addc_u32 s23, s5, 0
	s_add_u32 s24, s4, 0x1b800
	v_readlane_b32 s0, v252, 9
	s_addc_u32 s25, s5, 0
	v_lshlrev_b32_e32 v37, 2, v36
	s_lshl_b32 s34, s0, 2
	v_lshlrev_b32_e32 v38, 3, v36
	s_lshl_b32 s35, s0, 3
	s_mov_b64 s[26:27], 0
	s_branch .LBB0_20

; template <class Epi, class Sched, bool ALIGN_EPI = false, bool SP2 = false>
; __device__ __forceinline__ void gemm_phase(PG8_LAS unsigned char* lds, const Gemm g, const Sched& S, const Epi& E, int wave_in) {
;     ...
;     for (int i = 0; i < 2; ++i) { int R, C; stage_rc(tid * 16 + i * 8192, R, C); const int Rb = Epi::PERM ? ((R & ~31) + perm32(R & 31)) : R;
;         voffA[i] = (unsigned)(R * g.lda + C) * 2u; voffB[i] = (unsigned)(Rb * K + C) * 2u; }
;     const size_t kstep = (size_t)(BK * 2);
;     const size_t hstep = (size_t)HALF * K * 2;
;     const size_t tstep = 2 * hstep; const size_t hstepA = (size_t)HALF * g.lda * 2, tstepA = 2 * hstepA;
;     const unsigned ldsw = (unsigned)wid * 1024u;
;     const int aoff = lds_byte(wr * 64 + fr, fq * 8), boff = lds_byte(wc * 32 + fr, fq * 8);
; __global__ void __launch_bounds__(NTHR, 2) fwd(Args a) {
;     ...
;             else if (sp == 5) {
;                 { pg8::Epi<pg8::EP_MERGE0> E{MRG, D, nullptr, PROJ + 3072, INW, nullptr}; run_gemm<pg8::EP_MERGE0>(lds, YCAT, D, (const bf16_t*)(wl + O_WA), M, D, 1024, E, wave); }
; #pragma unroll 1
;                 for (int j = 1; j < 3; ++j) { pg8::Epi<pg8::EP_MERGE1> E{MRG, D, nullptr, PROJ + 3072 + j * D, INW, nullptr};
;                     run_gemm<pg8::EP_MERGE1>(lds, YCAT + 512 + 512 * j, D, (const bf16_t*)(wl + (j == 1 ? O_WSG : O_WSSM)), M, D, 512, E, wave); }
;             }
;             else if (sp == 7) { pg8::Epi<pg8::EP_UPCONV> E{ACT, DFF, ap->in[27] + (size_t)l * 3 * NUP, nullptr, 0, ap->in[28] + (size_t)l * NUP, RAW, SS + (size_t)(2 * l + 1) * M, nullptr, nullptr};
;                 run_gemm<pg8::EP_UPCONV>(lds, XB, D, (const bf16_t*)(wl + O_WUP), M, NUP, D, E, wave); }
;             else if (sp == 8) fixup_phase(RAW, ACT, ap->in[27] + (size_t)l * 3 * NUP, ap->in[28] + (size_t)l * NUP, blockIdx.x * NTHR + tid, G * NTHR);
;             else {
;                 const bf16_t* A; const bf16_t* Bt; int K; float* sso;
;                 if (sp == 6) { A = MRG; Bt = (const bf16_t*)(wl + O_WOUT); K = D; sso = SS + (size_t)(2 * l + 1) * M; }
;                 else { A = ACT; Bt = (const bf16_t*)(wl + O_WDN); K = DFF; sso = (l == 0) ? SS + (size_t)2 * M : nullptr; }
;                 pg8::Epi<pg8::EP_RESID> E{sso ? nullptr : ap->out, D, nullptr, nullptr, 0, nullptr, nullptr, nullptr, XB, sso};
;                 run_gemm<pg8::EP_RESID>(lds, A, K, Bt, M, D, K, E, wave);
.LBB0_70:
	s_cmp_gt_i32 s77, 4
	s_mov_b64 s[0:1], -1
	s_cbranch_scc0 .LBB0_114
	s_waitcnt lgkmcnt(0)
	s_add_u32 s0, s28, 0x2400000
	s_addc_u32 s1, s29, 0
	v_writelane_b32 v254, s0, 14
	s_nop 1
	v_writelane_b32 v254, s1, 15
	s_nop 1
	v_writelane_b32 v254, s0, 16
	s_nop 1
	v_writelane_b32 v254, s1, 17
	s_add_u32 s88, s28, 0x21700000
	s_addc_u32 s89, s29, 0
	s_mov_b64 s[0:1], -1
	v_writelane_b32 v254, s0, 2
	s_nop 1
	v_writelane_b32 v254, s1, 3
	s_mov_b32 s100, 1
	s_branch .LBB0_135
	v_readlane_b32 s2, v252, 13
	v_readlane_b32 s3, v252, 14
	s_waitcnt lgkmcnt(0)
	s_add_u32 s6, s28, 0xf701800
	v_mov_b32_e32 v2, v195
	v_cndmask_b32_e64 v0, 0, 1, s[2:3]
	s_addc_u32 s7, s29, 0
	v_cmp_ne_u32_e64 s[0:1], 1, v0
	s_andn2_b64 vcc, exec, s[2:3]
	v_readfirstlane_b32 s4, v2
	s_cbranch_vccnz .LBB0_91
	v_lshlrev_b32_e32 v0, 4, v2
	v_add_u32_e32 v4, 0x2000, v0
	v_ashrrev_i32_e32 v3, 31, v4
	v_lshrrev_b32_e32 v3, 22, v3
	v_add_u32_e32 v3, v4, v3
	v_ashrrev_i32_e32 v3, 10, v3
	v_mul_i32_i24_e32 v5, 0x400, v3
	v_sub_u32_e32 v4, v4, v5
	v_lshrrev_b32_e32 v5, 4, v4
	v_bitop3_b32 v5, v5, v4, 32 bitop3:0x6c
	v_ashrrev_i32_e32 v4, 31, v5
	v_lshrrev_b32_e32 v4, 26, v4
	v_add_u32_e32 v6, v5, v4
	v_lshlrev_b32_e32 v7, 3, v3
	v_ashrrev_i32_e32 v4, 6, v6
	v_and_b32_e32 v7, -16, v7
	v_add_u32_e32 v7, v4, v7
	v_and_b32_e32 v8, 3, v4
	s_mov_b32 s2, 0x1fffe0
	v_lshrrev_b32_e32 v9, 2, v7
	v_lshlrev_b32_e32 v10, 1, v7
	v_and_b32_e32 v6, 0xc0, v6
	v_and_or_b32 v8, v7, s2, v8
	v_and_b32_e32 v9, 4, v9
	v_and_b32_e32 v10, 24, v10
	v_sub_u32_e32 v5, v5, v6
	v_or3_b32 v8, v8, v9, v10
	v_lshlrev_b32_e32 v9, 5, v3
	v_ashrrev_i16_sdwa v5, v202, sext(v5) dst_sel:DWORD dst_unused:UNUSED_PAD src0_sel:DWORD src1_sel:BYTE_0
	v_and_b32_e32 v9, 32, v9
	v_bfe_i32 v5, v5, 0, 16
	v_add_lshl_u32 v6, v9, v5, 1
	v_lshl_add_u32 v130, v8, 11, v6
	v_lshl_add_u32 v132, v7, 12, v6
	v_bfe_i32 v6, v2, 27, 1
	v_lshrrev_b32_e32 v6, 22, v6
	v_add_u32_e32 v6, v0, v6
	v_and_b32_e32 v6, 0xfffffc00, v6
	v_sub_u32_e32 v0, v0, v6
	v_lshrrev_b32_e32 v6, 4, v0
	v_ashrrev_i32_e32 v7, 31, v2
	v_bitop3_b32 v0, v6, v0, 32 bitop3:0x6c
	v_lshrrev_b32_e32 v7, 26, v7
	v_ashrrev_i32_e32 v6, 31, v0
	v_add_u32_e32 v7, v2, v7
	v_lshrrev_b32_e32 v6, 26, v6
	v_ashrrev_i32_e32 v7, 6, v7
	v_add_u32_e32 v8, v0, v6
	v_lshlrev_b32_e32 v9, 3, v7
	v_ashrrev_i32_e32 v6, 6, v8
	v_and_b32_e32 v9, -16, v9
	v_add_u32_e32 v9, v6, v9
	s_add_u32 s28, s28, 0x2400000
	v_and_b32_e32 v10, 3, v6
	v_lshrrev_b32_e32 v11, 2, v9
	v_lshlrev_b32_e32 v12, 1, v9
	v_and_b32_e32 v8, 0xc0, v8
	s_addc_u32 s29, s29, 0
	s_ashr_i32 s8, s4, 6
	v_and_or_b32 v10, v9, s2, v10
	v_and_b32_e32 v11, 4, v11
	v_and_b32_e32 v12, 24, v12
	v_sub_u32_e32 v0, v0, v8
	s_ashr_i32 s5, s4, 8
	s_lshl_b32 s30, s8, 10
	v_or3_b32 v10, v10, v11, v12
	v_lshlrev_b32_e32 v11, 5, v7
	v_ashrrev_i16_sdwa v0, v202, sext(v0) dst_sel:DWORD dst_unused:UNUSED_PAD src0_sel:DWORD src1_sel:BYTE_0
	v_readlane_b32 s2, v253, 11
	v_and_b32_e32 v11, 32, v11
	v_bfe_i32 v8, v0, 0, 16
	v_readlane_b32 s3, v253, 12
	s_add_u32 s24, s28, s2
	v_add_lshl_u32 v11, v11, v8, 1
	s_addc_u32 s25, s29, s3
	s_add_i32 s31, s30, 0
	v_lshl_add_u32 v0, v10, 11, v11
	s_add_i32 m0, s31, 0x10000
	v_readlane_b32 s10, v253, 62
	global_load_lds_dwordx4 v0, s[24:25]
	s_add_i32 m0, s31, 0x12000
	s_add_u32 s2, s24, 0x40000
	global_load_lds_dwordx4 v130, s[24:25]
	s_addc_u32 s3, s25, 0
	s_add_i32 m0, s31, 0x14000
	v_readlane_b32 s11, v253, 63
	global_load_lds_dwordx4 v0, s[2:3]
	s_add_i32 m0, s31, 0x16000
	v_lshl_add_u32 v134, v9, 12, v11
	global_load_lds_dwordx4 v130, s[2:3]
	v_readlane_b32 s2, v253, 9
	v_readlane_b32 s3, v253, 10
	s_add_u32 s22, s10, s2
	s_addc_u32 s23, s11, s3
	s_add_i32 s34, s31, 0x2000
	s_mov_b32 m0, s31
	s_add_u32 s2, s22, 0x80000
	global_load_lds_dwordx4 v134, s[22:23]
	s_mov_b32 m0, s34
	s_addc_u32 s3, s23, 0
	s_add_i32 s35, s31, 0x4000
	global_load_lds_dwordx4 v132, s[22:23]
	s_mov_b32 m0, s35
	s_add_i32 s36, s31, 0x6000
	global_load_lds_dwordx4 v134, s[2:3]
	s_mov_b32 m0, s36
	s_cmp_eq_u32 s5, 1
	global_load_lds_dwordx4 v132, s[2:3]
	s_cselect_b64 s[2:3], -1, 0
	s_cmp_lg_u32 s5, 1
	s_cbranch_scc1 .LBB0_74
	s_barrier

; template <class Epi, class Sched, bool ALIGN_EPI = false, bool SP2 = false>
; __device__ __forceinline__ void gemm_phase(PG8_LAS unsigned char* lds, const Gemm g, const Sched& S, const Epi& E, int wave_in) {
;     ...
;         for (int t = 0; t < nt; t += 2) {
;             const bool last = (t == nt - 2);
;             const char* a1 = cA + (size_t)(t + 1) * kstep;
;             const char* a2 = last ? nA : cA + (size_t)(t + 2) * kstep; const char* b2 = last ? nB : cB + (size_t)(t + 2) * kstep;
;             const char* a3 = a2 + kstep; const char* b3 = b2 + kstep;
;             if (last && has_next) S.a_ready(nxt);
.LBB0_404:
	s_cmp_eq_u32 s100, 1
	s_cbranch_scc0 .Lmg_nohook
	s_cmp_eq_u32 s6, 16
	s_cbranch_scc1 .Lmg_rescale01
	s_cmp_eq_u32 s6, 24
	s_cbranch_scc1 .Lmg_rescale12

; __device__ __forceinline__ void unpack8(u32x4 w, f32x4& a, f32x4& b) { a = (f32x4){bf_lo(w.x), bf_hi(w.x), bf_lo(w.y), bf_hi(w.y)}; b = (f32x4){bf_lo(w.z), bf_hi(w.z), bf_lo(w.w), bf_hi(w.w)}; }
;     __device__ __forceinline__ void operator()(const f32x4 (&acc)[2][2][4][2], const Unit& u, int wr, int wc, int fr, int fq) const {
;     ...
;                     } else if (MODE == EP_RESID) {
;                         f32x4 x0, x1; unpack8(*(const u32x4*)(xb + row * ldc + col), x0, x1); x0 = x0 + v0; x1 = x1 + v1;
;                         if (O) { *(f32x4*)((float*)O + row * ldc + col) = x0; *(f32x4*)((float*)O + row * ldc + col + 4) = x1; }
.LBB0_407:
	s_cmp_eq_u32 s100, 1
	s_cbranch_scc1 .Lmg_epilogue
	v_lshl_add_u32 v140, s42, 8, v148
	v_ashrrev_i32_e32 v141, 31, v140
	v_readlane_b32 s4, v253, 60
	v_lshl_or_b32 v142, s41, 8, v152
	v_lshlrev_b64 v[144:145], 12, v[140:141]
	v_readlane_b32 s5, v253, 61
	v_ashrrev_i32_e32 v143, 31, v142
	v_cndmask_b32_e64 v146, 0, 1, s[18:19]
	v_lshl_add_u64 v[144:145], s[4:5], 0, v[144:145]
	v_lshl_add_u64 v[144:145], v[142:143], 1, v[144:145]
	global_load_dwordx4 v[154:157], v[144:145], off
	v_cmp_ne_u32_e64 s[4:5], 1, v146
	v_lshlrev_b64 v[146:147], 11, v[140:141]
	s_andn2_b64 vcc, exec, s[18:19]
	v_lshl_add_u64 v[146:147], v[146:147], 2, s[2:3]
	s_waitcnt vmcnt(0)
	v_lshlrev_b32_e32 v168, 16, v154
	v_and_b32_e32 v169, 0xffff0000, v154
	v_lshlrev_b32_e32 v154, 16, v155
	v_and_b32_e32 v155, 0xffff0000, v155
	v_lshlrev_b32_e32 v170, 16, v156
	v_and_b32_e32 v171, 0xffff0000, v156
	v_lshlrev_b32_e32 v156, 16, v157
	v_and_b32_e32 v157, 0xffff0000, v157
	v_pk_add_f32 v[128:129], v[128:129], v[154:155]
	v_pk_add_f32 v[126:127], v[126:127], v[168:169]
	v_pk_add_f32 v[124:125], v[124:125], v[156:157]
	v_pk_add_f32 v[122:123], v[122:123], v[170:171]
	s_cbranch_vccnz .LBB0_409
	v_lshl_add_u64 v[154:155], v[142:143], 2, v[146:147]
	global_store_dwordx4 v[154:155], v[126:129], off
	global_store_dwordx4 v[154:155], v[122:125], off offset:16

; __device__ __forceinline__ void unpack8(u32x4 w, f32x4& a, f32x4& b) { a = (f32x4){bf_lo(w.x), bf_hi(w.x), bf_lo(w.y), bf_hi(w.y)}; b = (f32x4){bf_lo(w.z), bf_hi(w.z), bf_lo(w.w), bf_hi(w.w)}; }
;     __device__ __forceinline__ void operator()(const f32x4 (&acc)[2][2][4][2], const Unit& u, int wr, int wc, int fr, int fq) const {
;     ...
;                     } else if (MODE == EP_MERGE0 || MODE == EP_MERGE1) {
;                         f32x4 g0, g1; unpack8(*(const u32x4*)(aux + row * ldaux + col), g0, g1);
;                         v0 = g0 * v0; v1 = g1 * v1;
.Lmg_rescale01:
	v_lshl_add_u32 v166, s42, 8, v148
	v_lshl_or_b32 v167, s41, 8, v152
	v_lshlrev_b32_e32 v167, 1, v167
	v_add_u32_e32 v167, 0x1800, v167
	v_add_u32_e32 v199, 0, v166
	v_mad_u32_u24 v205, v199, s81, v167
	v_add_u32_e32 v250, 0x1000, v205
	global_load_dwordx4 v[140:143], v205, s[68:69]
	global_load_dwordx4 v[144:147], v250, s[68:69]
	global_load_dwordx4 v[154:157], v205, s[68:69] offset:256
	global_load_dwordx4 v[168:171], v250, s[68:69] offset:256
	v_add_u32_e32 v199, 16, v166
	v_mad_u32_u24 v205, v199, s81, v167
	v_add_u32_e32 v250, 0x1000, v205
	global_load_dwordx4 v[172:175], v205, s[68:69]
	global_load_dwordx4 v[176:179], v250, s[68:69]
	global_load_dwordx4 v[180:183], v205, s[68:69] offset:256
	global_load_dwordx4 v[184:187], v250, s[68:69] offset:256
	v_add_u32_e32 v199, 32, v166
	v_mad_u32_u24 v205, v199, s81, v167
	v_add_u32_e32 v250, 0x1000, v205
	global_load_dwordx4 v[188:191], v205, s[68:69]
	global_load_dwordx4 v[212:215], v250, s[68:69]
	global_load_dwordx4 v[216:219], v205, s[68:69] offset:256
	global_load_dwordx4 v[220:223], v250, s[68:69] offset:256
	v_add_u32_e32 v199, 48, v166
	v_mad_u32_u24 v205, v199, s81, v167
	v_add_u32_e32 v250, 0x1000, v205
	global_load_dwordx4 v[224:227], v205, s[68:69]
	global_load_dwordx4 v[228:231], v250, s[68:69]
	global_load_dwordx4 v[232:235], v205, s[68:69] offset:256
	global_load_dwordx4 v[236:239], v250, s[68:69] offset:256
	s_waitcnt vmcnt(14)
	v_lshlrev_b32_e32 v206, 16, v144
	v_and_b32_e32 v207, 0xffff0000, v144
	v_max_f32_e32 v206, 0x2b800000, v206
	v_max_f32_e32 v207, 0x2b800000, v207
	v_rcp_f32_e32 v206, v206
	v_rcp_f32_e32 v207, v207
	v_lshlrev_b32_e32 v144, 16, v140
	v_and_b32_e32 v140, 0xffff0000, v140
	v_mul_f32_e32 v206, v206, v144
	v_mul_f32_e32 v207, v207, v140
	v_mul_f32_e32 v126, v126, v206
	v_mul_f32_e32 v127, v127, v207
	v_lshlrev_b32_e32 v208, 16, v145
	v_and_b32_e32 v209, 0xffff0000, v145
	v_max_f32_e32 v208, 0x2b800000, v208
	v_max_f32_e32 v209, 0x2b800000, v209
	v_rcp_f32_e32 v208, v208
	v_rcp_f32_e32 v209, v209
	v_lshlrev_b32_e32 v145, 16, v141
	v_and_b32_e32 v141, 0xffff0000, v141
	v_mul_f32_e32 v208, v208, v145
	v_mul_f32_e32 v209, v209, v141
	v_mul_f32_e32 v128, v128, v208
	v_mul_f32_e32 v129, v129, v209
	v_lshlrev_b32_e32 v210, 16, v146
	v_and_b32_e32 v211, 0xffff0000, v146
	v_max_f32_e32 v210, 0x2b800000, v210
	v_max_f32_e32 v211, 0x2b800000, v211
	v_rcp_f32_e32 v210, v210
	v_rcp_f32_e32 v211, v211
	v_lshlrev_b32_e32 v146, 16, v142
	v_and_b32_e32 v142, 0xffff0000, v142
	v_mul_f32_e32 v210, v210, v146
	v_mul_f32_e32 v211, v211, v142
	v_mul_f32_e32 v122, v122, v210
	v_mul_f32_e32 v123, v123, v211
	v_lshlrev_b32_e32 v206, 16, v147
	v_and_b32_e32 v207, 0xffff0000, v147
	v_max_f32_e32 v206, 0x2b800000, v206
	v_max_f32_e32 v207, 0x2b800000, v207
	v_rcp_f32_e32 v206, v206
	v_rcp_f32_e32 v207, v207
	v_lshlrev_b32_e32 v147, 16, v143
	v_and_b32_e32 v143, 0xffff0000, v143
	v_mul_f32_e32 v206, v206, v147
	v_mul_f32_e32 v207, v207, v143
	v_mul_f32_e32 v124, v124, v206
	v_mul_f32_e32 v125, v125, v207
	s_waitcnt vmcnt(12)
	v_lshlrev_b32_e32 v206, 16, v168
	v_and_b32_e32 v207, 0xffff0000, v168
	v_max_f32_e32 v206, 0x2b800000, v206
	v_max_f32_e32 v207, 0x2b800000, v207
	v_rcp_f32_e32 v206, v206
	v_rcp_f32_e32 v207, v207
	v_lshlrev_b32_e32 v168, 16, v154
	v_and_b32_e32 v154, 0xffff0000, v154
	v_mul_f32_e32 v206, v206, v168
	v_mul_f32_e32 v207, v207, v154
	v_mul_f32_e32 v118, v118, v206
	v_mul_f32_e32 v119, v119, v207
	v_lshlrev_b32_e32 v208, 16, v169
	v_and_b32_e32 v209, 0xffff0000, v169
	v_max_f32_e32 v208, 0x2b800000, v208
	v_max_f32_e32 v209, 0x2b800000, v209
	v_rcp_f32_e32 v208, v208
	v_rcp_f32_e32 v209, v209
	v_lshlrev_b32_e32 v169, 16, v155
	v_and_b32_e32 v155, 0xffff0000, v155
	v_mul_f32_e32 v208, v208, v169
	v_mul_f32_e32 v209, v209, v155
	v_mul_f32_e32 v120, v120, v208
	v_mul_f32_e32 v121, v121, v209
	v_lshlrev_b32_e32 v210, 16, v170
	v_and_b32_e32 v211, 0xffff0000, v170
	v_max_f32_e32 v210, 0x2b800000, v210
	v_max_f32_e32 v211, 0x2b800000, v211
	v_rcp_f32_e32 v210, v210
	v_rcp_f32_e32 v211, v211
	v_lshlrev_b32_e32 v170, 16, v156
	v_and_b32_e32 v156, 0xffff0000, v156
	v_mul_f32_e32 v210, v210, v170
	v_mul_f32_e32 v211, v211, v156
	v_mul_f32_e32 v114, v114, v210
	v_mul_f32_e32 v115, v115, v211
	v_lshlrev_b32_e32 v206, 16, v171
	v_and_b32_e32 v207, 0xffff0000, v171
	v_max_f32_e32 v206, 0x2b800000, v206
	v_max_f32_e32 v207, 0x2b800000, v207
	v_rcp_f32_e32 v206, v206
	v_rcp_f32_e32 v207, v207
	v_lshlrev_b32_e32 v171, 16, v157
	v_and_b32_e32 v157, 0xffff0000, v157
	v_mul_f32_e32 v206, v206, v171
	v_mul_f32_e32 v207, v207, v157
	v_mul_f32_e32 v116, v116, v206
	v_mul_f32_e32 v117, v117, v207
	v_add_u32_e32 v199, 128, v166
	v_mad_u32_u24 v205, v199, s81, v167
	v_add_u32_e32 v250, 0x1000, v205
	global_load_dwordx4 v[140:143], v205, s[68:69]
	global_load_dwordx4 v[144:147], v250, s[68:69]
	global_load_dwordx4 v[154:157], v205, s[68:69] offset:256
	global_load_dwordx4 v[168:171], v250, s[68:69] offset:256
	s_waitcnt vmcnt(14)
; __device__ __forceinline__ void unpack8(u32x4 w, f32x4& a, f32x4& b) { a = (f32x4){bf_lo(w.x), bf_hi(w.x), bf_lo(w.y), bf_hi(w.y)}; b = (f32x4){bf_lo(w.z), bf_hi(w.z), bf_lo(w.w), bf_hi(w.w)}; }
;     __device__ __forceinline__ void operator()(const f32x4 (&acc)[2][2][4][2], const Unit& u, int wr, int wc, int fr, int fq) const {
;     ...
;                     } else if (MODE == EP_MERGE0 || MODE == EP_MERGE1) {
;                         f32x4 g0, g1; unpack8(*(const u32x4*)(aux + row * ldaux + col), g0, g1);
;                         v0 = g0 * v0; v1 = g1 * v1;
	v_lshlrev_b32_e32 v206, 16, v176
	v_and_b32_e32 v207, 0xffff0000, v176
	v_max_f32_e32 v206, 0x2b800000, v206
	v_max_f32_e32 v207, 0x2b800000, v207
	v_rcp_f32_e32 v206, v206
	v_rcp_f32_e32 v207, v207
	v_lshlrev_b32_e32 v176, 16, v172
	v_and_b32_e32 v172, 0xffff0000, v172
	v_mul_f32_e32 v206, v206, v176
	v_mul_f32_e32 v207, v207, v172
	v_mul_f32_e32 v110, v110, v206
	v_mul_f32_e32 v111, v111, v207
	v_lshlrev_b32_e32 v208, 16, v177
	v_and_b32_e32 v209, 0xffff0000, v177
	v_max_f32_e32 v208, 0x2b800000, v208
	v_max_f32_e32 v209, 0x2b800000, v209
	v_rcp_f32_e32 v208, v208
	v_rcp_f32_e32 v209, v209
	v_lshlrev_b32_e32 v177, 16, v173
	v_and_b32_e32 v173, 0xffff0000, v173
	v_mul_f32_e32 v208, v208, v177
	v_mul_f32_e32 v209, v209, v173
	v_mul_f32_e32 v112, v112, v208
	v_mul_f32_e32 v113, v113, v209
	v_lshlrev_b32_e32 v210, 16, v178
	v_and_b32_e32 v211, 0xffff0000, v178
	v_max_f32_e32 v210, 0x2b800000, v210
	v_max_f32_e32 v211, 0x2b800000, v211
	v_rcp_f32_e32 v210, v210
	v_rcp_f32_e32 v211, v211
	v_lshlrev_b32_e32 v178, 16, v174
	v_and_b32_e32 v174, 0xffff0000, v174
	v_mul_f32_e32 v210, v210, v178
	v_mul_f32_e32 v211, v211, v174
	v_mul_f32_e32 v106, v106, v210
	v_mul_f32_e32 v107, v107, v211
	v_lshlrev_b32_e32 v206, 16, v179
	v_and_b32_e32 v207, 0xffff0000, v179
	v_max_f32_e32 v206, 0x2b800000, v206
	v_max_f32_e32 v207, 0x2b800000, v207
	v_rcp_f32_e32 v206, v206
	v_rcp_f32_e32 v207, v207
	v_lshlrev_b32_e32 v179, 16, v175
	v_and_b32_e32 v175, 0xffff0000, v175
	v_mul_f32_e32 v206, v206, v179
	v_mul_f32_e32 v207, v207, v175
	v_mul_f32_e32 v108, v108, v206
	v_mul_f32_e32 v109, v109, v207
	s_waitcnt vmcnt(12)
	v_lshlrev_b32_e32 v206, 16, v184
	v_and_b32_e32 v207, 0xffff0000, v184
	v_max_f32_e32 v206, 0x2b800000, v206
	v_max_f32_e32 v207, 0x2b800000, v207
	v_rcp_f32_e32 v206, v206
	v_rcp_f32_e32 v207, v207
	v_lshlrev_b32_e32 v184, 16, v180
	v_and_b32_e32 v180, 0xffff0000, v180
	v_mul_f32_e32 v206, v206, v184
	v_mul_f32_e32 v207, v207, v180
	v_mul_f32_e32 v102, v102, v206
	v_mul_f32_e32 v103, v103, v207
	v_lshlrev_b32_e32 v208, 16, v185
	v_and_b32_e32 v209, 0xffff0000, v185
	v_max_f32_e32 v208, 0x2b800000, v208
	v_max_f32_e32 v209, 0x2b800000, v209
	v_rcp_f32_e32 v208, v208
	v_rcp_f32_e32 v209, v209
	v_lshlrev_b32_e32 v185, 16, v181
	v_and_b32_e32 v181, 0xffff0000, v181
	v_mul_f32_e32 v208, v208, v185
	v_mul_f32_e32 v209, v209, v181
	v_mul_f32_e32 v104, v104, v208
	v_mul_f32_e32 v105, v105, v209
	v_lshlrev_b32_e32 v210, 16, v186
	v_and_b32_e32 v211, 0xffff0000, v186
	v_max_f32_e32 v210, 0x2b800000, v210
	v_max_f32_e32 v211, 0x2b800000, v211
	v_rcp_f32_e32 v210, v210
	v_rcp_f32_e32 v211, v211
	v_lshlrev_b32_e32 v186, 16, v182
	v_and_b32_e32 v182, 0xffff0000, v182
	v_mul_f32_e32 v210, v210, v186
	v_mul_f32_e32 v211, v211, v182
	v_mul_f32_e32 v98, v98, v210
	v_mul_f32_e32 v99, v99, v211
	v_lshlrev_b32_e32 v206, 16, v187
	v_and_b32_e32 v207, 0xffff0000, v187
	v_max_f32_e32 v206, 0x2b800000, v206
	v_max_f32_e32 v207, 0x2b800000, v207
	v_rcp_f32_e32 v206, v206
	v_rcp_f32_e32 v207, v207
	v_lshlrev_b32_e32 v187, 16, v183
	v_and_b32_e32 v183, 0xffff0000, v183
	v_mul_f32_e32 v206, v206, v187
	v_mul_f32_e32 v207, v207, v183
	v_mul_f32_e32 v100, v100, v206
	v_mul_f32_e32 v101, v101, v207
	v_add_u32_e32 v199, 144, v166
	v_mad_u32_u24 v205, v199, s81, v167
	v_add_u32_e32 v250, 0x1000, v205
	global_load_dwordx4 v[172:175], v205, s[68:69]
	global_load_dwordx4 v[176:179], v250, s[68:69]
	global_load_dwordx4 v[180:183], v205, s[68:69] offset:256
	global_load_dwordx4 v[184:187], v250, s[68:69] offset:256
	s_waitcnt vmcnt(14)
	v_lshlrev_b32_e32 v206, 16, v212
	v_and_b32_e32 v207, 0xffff0000, v212
	v_max_f32_e32 v206, 0x2b800000, v206
	v_max_f32_e32 v207, 0x2b800000, v207
	v_rcp_f32_e32 v206, v206
	v_rcp_f32_e32 v207, v207
	v_lshlrev_b32_e32 v212, 16, v188
	v_and_b32_e32 v188, 0xffff0000, v188
	v_mul_f32_e32 v206, v206, v212
	v_mul_f32_e32 v207, v207, v188
	v_mul_f32_e32 v94, v94, v206
	v_mul_f32_e32 v95, v95, v207
	v_lshlrev_b32_e32 v208, 16, v213
	v_and_b32_e32 v209, 0xffff0000, v213
	v_max_f32_e32 v208, 0x2b800000, v208
	v_max_f32_e32 v209, 0x2b800000, v209
	v_rcp_f32_e32 v208, v208
	v_rcp_f32_e32 v209, v209
	v_lshlrev_b32_e32 v213, 16, v189
	v_and_b32_e32 v189, 0xffff0000, v189
	v_mul_f32_e32 v208, v208, v213
	v_mul_f32_e32 v209, v209, v189
	v_mul_f32_e32 v96, v96, v208
	v_mul_f32_e32 v97, v97, v209
	v_lshlrev_b32_e32 v210, 16, v214
	v_and_b32_e32 v211, 0xffff0000, v214
	v_max_f32_e32 v210, 0x2b800000, v210
	v_max_f32_e32 v211, 0x2b800000, v211
	v_rcp_f32_e32 v210, v210
	v_rcp_f32_e32 v211, v211
	v_lshlrev_b32_e32 v214, 16, v190
	v_and_b32_e32 v190, 0xffff0000, v190
	v_mul_f32_e32 v210, v210, v214
	v_mul_f32_e32 v211, v211, v190
	v_mul_f32_e32 v90, v90, v210
	v_mul_f32_e32 v91, v91, v211
	v_lshlrev_b32_e32 v206, 16, v215
	v_and_b32_e32 v207, 0xffff0000, v215
	v_max_f32_e32 v206, 0x2b800000, v206
	v_max_f32_e32 v207, 0x2b800000, v207
	v_rcp_f32_e32 v206, v206
	v_rcp_f32_e32 v207, v207
	v_lshlrev_b32_e32 v215, 16, v191
	v_and_b32_e32 v191, 0xffff0000, v191
	v_mul_f32_e32 v206, v206, v215
	v_mul_f32_e32 v207, v207, v191
	v_mul_f32_e32 v92, v92, v206
	v_mul_f32_e32 v93, v93, v207
	s_waitcnt vmcnt(12)
; __device__ __forceinline__ void unpack8(u32x4 w, f32x4& a, f32x4& b) { a = (f32x4){bf_lo(w.x), bf_hi(w.x), bf_lo(w.y), bf_hi(w.y)}; b = (f32x4){bf_lo(w.z), bf_hi(w.z), bf_lo(w.w), bf_hi(w.w)}; }
;     __device__ __forceinline__ void operator()(const f32x4 (&acc)[2][2][4][2], const Unit& u, int wr, int wc, int fr, int fq) const {
;     ...
;                     } else if (MODE == EP_MERGE0 || MODE == EP_MERGE1) {
;                         f32x4 g0, g1; unpack8(*(const u32x4*)(aux + row * ldaux + col), g0, g1);
;                         v0 = g0 * v0; v1 = g1 * v1;
	v_lshlrev_b32_e32 v206, 16, v220
	v_and_b32_e32 v207, 0xffff0000, v220
	v_max_f32_e32 v206, 0x2b800000, v206
	v_max_f32_e32 v207, 0x2b800000, v207
	v_rcp_f32_e32 v206, v206
	v_rcp_f32_e32 v207, v207
	v_lshlrev_b32_e32 v220, 16, v216
	v_and_b32_e32 v216, 0xffff0000, v216
	v_mul_f32_e32 v206, v206, v220
	v_mul_f32_e32 v207, v207, v216
	v_mul_f32_e32 v86, v86, v206
	v_mul_f32_e32 v87, v87, v207
	v_lshlrev_b32_e32 v208, 16, v221
	v_and_b32_e32 v209, 0xffff0000, v221
	v_max_f32_e32 v208, 0x2b800000, v208
	v_max_f32_e32 v209, 0x2b800000, v209
	v_rcp_f32_e32 v208, v208
	v_rcp_f32_e32 v209, v209
	v_lshlrev_b32_e32 v221, 16, v217
	v_and_b32_e32 v217, 0xffff0000, v217
	v_mul_f32_e32 v208, v208, v221
	v_mul_f32_e32 v209, v209, v217
	v_mul_f32_e32 v88, v88, v208
	v_mul_f32_e32 v89, v89, v209
	v_lshlrev_b32_e32 v210, 16, v222
	v_and_b32_e32 v211, 0xffff0000, v222
	v_max_f32_e32 v210, 0x2b800000, v210
	v_max_f32_e32 v211, 0x2b800000, v211
	v_rcp_f32_e32 v210, v210
	v_rcp_f32_e32 v211, v211
	v_lshlrev_b32_e32 v222, 16, v218
	v_and_b32_e32 v218, 0xffff0000, v218
	v_mul_f32_e32 v210, v210, v222
	v_mul_f32_e32 v211, v211, v218
	v_mul_f32_e32 v82, v82, v210
	v_mul_f32_e32 v83, v83, v211
	v_lshlrev_b32_e32 v206, 16, v223
	v_and_b32_e32 v207, 0xffff0000, v223
	v_max_f32_e32 v206, 0x2b800000, v206
	v_max_f32_e32 v207, 0x2b800000, v207
	v_rcp_f32_e32 v206, v206
	v_rcp_f32_e32 v207, v207
	v_lshlrev_b32_e32 v223, 16, v219
	v_and_b32_e32 v219, 0xffff0000, v219
	v_mul_f32_e32 v206, v206, v223
	v_mul_f32_e32 v207, v207, v219
	v_mul_f32_e32 v84, v84, v206
	v_mul_f32_e32 v85, v85, v207
	v_add_u32_e32 v199, 160, v166
	v_mad_u32_u24 v205, v199, s81, v167
	v_add_u32_e32 v250, 0x1000, v205
	global_load_dwordx4 v[188:191], v205, s[68:69]
	global_load_dwordx4 v[212:215], v250, s[68:69]
	global_load_dwordx4 v[216:219], v205, s[68:69] offset:256
	global_load_dwordx4 v[220:223], v250, s[68:69] offset:256
	s_waitcnt vmcnt(14)
	v_lshlrev_b32_e32 v206, 16, v228
	v_and_b32_e32 v207, 0xffff0000, v228
	v_max_f32_e32 v206, 0x2b800000, v206
	v_max_f32_e32 v207, 0x2b800000, v207
	v_rcp_f32_e32 v206, v206
	v_rcp_f32_e32 v207, v207
	v_lshlrev_b32_e32 v228, 16, v224
	v_and_b32_e32 v224, 0xffff0000, v224
	v_mul_f32_e32 v206, v206, v228
	v_mul_f32_e32 v207, v207, v224
	v_mul_f32_e32 v78, v78, v206
	v_mul_f32_e32 v79, v79, v207
	v_lshlrev_b32_e32 v208, 16, v229
	v_and_b32_e32 v209, 0xffff0000, v229
	v_max_f32_e32 v208, 0x2b800000, v208
	v_max_f32_e32 v209, 0x2b800000, v209
	v_rcp_f32_e32 v208, v208
	v_rcp_f32_e32 v209, v209
	v_lshlrev_b32_e32 v229, 16, v225
	v_and_b32_e32 v225, 0xffff0000, v225
	v_mul_f32_e32 v208, v208, v229
	v_mul_f32_e32 v209, v209, v225
	v_mul_f32_e32 v80, v80, v208
	v_mul_f32_e32 v81, v81, v209
	v_lshlrev_b32_e32 v210, 16, v230
	v_and_b32_e32 v211, 0xffff0000, v230
	v_max_f32_e32 v210, 0x2b800000, v210
	v_max_f32_e32 v211, 0x2b800000, v211
	v_rcp_f32_e32 v210, v210
	v_rcp_f32_e32 v211, v211
	v_lshlrev_b32_e32 v230, 16, v226
	v_and_b32_e32 v226, 0xffff0000, v226
	v_mul_f32_e32 v210, v210, v230
	v_mul_f32_e32 v211, v211, v226
	v_mul_f32_e32 v74, v74, v210
	v_mul_f32_e32 v75, v75, v211
	v_lshlrev_b32_e32 v206, 16, v231
	v_and_b32_e32 v207, 0xffff0000, v231
	v_max_f32_e32 v206, 0x2b800000, v206
	v_max_f32_e32 v207, 0x2b800000, v207
	v_rcp_f32_e32 v206, v206
	v_rcp_f32_e32 v207, v207
	v_lshlrev_b32_e32 v231, 16, v227
	v_and_b32_e32 v227, 0xffff0000, v227
	v_mul_f32_e32 v206, v206, v231
	v_mul_f32_e32 v207, v207, v227
	v_mul_f32_e32 v76, v76, v206
	v_mul_f32_e32 v77, v77, v207
	s_waitcnt vmcnt(12)
	v_lshlrev_b32_e32 v206, 16, v236
	v_and_b32_e32 v207, 0xffff0000, v236
	v_max_f32_e32 v206, 0x2b800000, v206
	v_max_f32_e32 v207, 0x2b800000, v207
	v_rcp_f32_e32 v206, v206
	v_rcp_f32_e32 v207, v207
	v_lshlrev_b32_e32 v236, 16, v232
	v_and_b32_e32 v232, 0xffff0000, v232
	v_mul_f32_e32 v206, v206, v236
	v_mul_f32_e32 v207, v207, v232
	v_mul_f32_e32 v70, v70, v206
	v_mul_f32_e32 v71, v71, v207
	v_lshlrev_b32_e32 v208, 16, v237
	v_and_b32_e32 v209, 0xffff0000, v237
	v_max_f32_e32 v208, 0x2b800000, v208
	v_max_f32_e32 v209, 0x2b800000, v209
	v_rcp_f32_e32 v208, v208
	v_rcp_f32_e32 v209, v209
	v_lshlrev_b32_e32 v237, 16, v233
	v_and_b32_e32 v233, 0xffff0000, v233
	v_mul_f32_e32 v208, v208, v237
	v_mul_f32_e32 v209, v209, v233
	v_mul_f32_e32 v72, v72, v208
	v_mul_f32_e32 v73, v73, v209
	v_lshlrev_b32_e32 v210, 16, v238
	v_and_b32_e32 v211, 0xffff0000, v238
	v_max_f32_e32 v210, 0x2b800000, v210
	v_max_f32_e32 v211, 0x2b800000, v211
	v_rcp_f32_e32 v210, v210
	v_rcp_f32_e32 v211, v211
	v_lshlrev_b32_e32 v238, 16, v234
	v_and_b32_e32 v234, 0xffff0000, v234
	v_mul_f32_e32 v210, v210, v238
	v_mul_f32_e32 v211, v211, v234
	v_mul_f32_e32 v66, v66, v210
	v_mul_f32_e32 v67, v67, v211
	v_lshlrev_b32_e32 v206, 16, v239
	v_and_b32_e32 v207, 0xffff0000, v239
	v_max_f32_e32 v206, 0x2b800000, v206
	v_max_f32_e32 v207, 0x2b800000, v207
	v_rcp_f32_e32 v206, v206
	v_rcp_f32_e32 v207, v207
	v_lshlrev_b32_e32 v239, 16, v235
	v_and_b32_e32 v235, 0xffff0000, v235
	v_mul_f32_e32 v206, v206, v239
	v_mul_f32_e32 v207, v207, v235
	v_mul_f32_e32 v68, v68, v206
	v_mul_f32_e32 v69, v69, v207
	v_add_u32_e32 v199, 176, v166
	v_mad_u32_u24 v205, v199, s81, v167
	v_add_u32_e32 v250, 0x1000, v205
	global_load_dwordx4 v[224:227], v205, s[68:69]
	global_load_dwordx4 v[228:231], v250, s[68:69]
	global_load_dwordx4 v[232:235], v205, s[68:69] offset:256
	global_load_dwordx4 v[236:239], v250, s[68:69] offset:256
	s_waitcnt vmcnt(14)
; __device__ __forceinline__ void unpack8(u32x4 w, f32x4& a, f32x4& b) { a = (f32x4){bf_lo(w.x), bf_hi(w.x), bf_lo(w.y), bf_hi(w.y)}; b = (f32x4){bf_lo(w.z), bf_hi(w.z), bf_lo(w.w), bf_hi(w.w)}; }
;     __device__ __forceinline__ void operator()(const f32x4 (&acc)[2][2][4][2], const Unit& u, int wr, int wc, int fr, int fq) const {
;     ...
;                     } else if (MODE == EP_MERGE0 || MODE == EP_MERGE1) {
;                         f32x4 g0, g1; unpack8(*(const u32x4*)(aux + row * ldaux + col), g0, g1);
;                         v0 = g0 * v0; v1 = g1 * v1;
	v_lshlrev_b32_e32 v206, 16, v144
	v_and_b32_e32 v207, 0xffff0000, v144
	v_max_f32_e32 v206, 0x2b800000, v206
	v_max_f32_e32 v207, 0x2b800000, v207
	v_rcp_f32_e32 v206, v206
	v_rcp_f32_e32 v207, v207
	v_lshlrev_b32_e32 v144, 16, v140
	v_and_b32_e32 v140, 0xffff0000, v140
	v_mul_f32_e32 v206, v206, v144
	v_mul_f32_e32 v207, v207, v140
	v_mul_f32_e32 v62, v62, v206
	v_mul_f32_e32 v63, v63, v207
	v_lshlrev_b32_e32 v208, 16, v145
	v_and_b32_e32 v209, 0xffff0000, v145
	v_max_f32_e32 v208, 0x2b800000, v208
	v_max_f32_e32 v209, 0x2b800000, v209
	v_rcp_f32_e32 v208, v208
	v_rcp_f32_e32 v209, v209
	v_lshlrev_b32_e32 v145, 16, v141
	v_and_b32_e32 v141, 0xffff0000, v141
	v_mul_f32_e32 v208, v208, v145
	v_mul_f32_e32 v209, v209, v141
	v_mul_f32_e32 v64, v64, v208
	v_mul_f32_e32 v65, v65, v209
	v_lshlrev_b32_e32 v210, 16, v146
	v_and_b32_e32 v211, 0xffff0000, v146
	v_max_f32_e32 v210, 0x2b800000, v210
	v_max_f32_e32 v211, 0x2b800000, v211
	v_rcp_f32_e32 v210, v210
	v_rcp_f32_e32 v211, v211
	v_lshlrev_b32_e32 v146, 16, v142
	v_and_b32_e32 v142, 0xffff0000, v142
	v_mul_f32_e32 v210, v210, v146
	v_mul_f32_e32 v211, v211, v142
	v_mul_f32_e32 v58, v58, v210
	v_mul_f32_e32 v59, v59, v211
	v_lshlrev_b32_e32 v206, 16, v147
	v_and_b32_e32 v207, 0xffff0000, v147
	v_max_f32_e32 v206, 0x2b800000, v206
	v_max_f32_e32 v207, 0x2b800000, v207
	v_rcp_f32_e32 v206, v206
	v_rcp_f32_e32 v207, v207
	v_lshlrev_b32_e32 v147, 16, v143
	v_and_b32_e32 v143, 0xffff0000, v143
	v_mul_f32_e32 v206, v206, v147
	v_mul_f32_e32 v207, v207, v143
	v_mul_f32_e32 v60, v60, v206
	v_mul_f32_e32 v61, v61, v207
	s_waitcnt vmcnt(12)
	v_lshlrev_b32_e32 v206, 16, v168
	v_and_b32_e32 v207, 0xffff0000, v168
	v_max_f32_e32 v206, 0x2b800000, v206
	v_max_f32_e32 v207, 0x2b800000, v207
	v_rcp_f32_e32 v206, v206
	v_rcp_f32_e32 v207, v207
	v_lshlrev_b32_e32 v168, 16, v154
	v_and_b32_e32 v154, 0xffff0000, v154
	v_mul_f32_e32 v206, v206, v168
	v_mul_f32_e32 v207, v207, v154
	v_mul_f32_e32 v54, v54, v206
	v_mul_f32_e32 v55, v55, v207
	v_lshlrev_b32_e32 v208, 16, v169
	v_and_b32_e32 v209, 0xffff0000, v169
	v_max_f32_e32 v208, 0x2b800000, v208
	v_max_f32_e32 v209, 0x2b800000, v209
	v_rcp_f32_e32 v208, v208
	v_rcp_f32_e32 v209, v209
	v_lshlrev_b32_e32 v169, 16, v155
	v_and_b32_e32 v155, 0xffff0000, v155
	v_mul_f32_e32 v208, v208, v169
	v_mul_f32_e32 v209, v209, v155
	v_mul_f32_e32 v56, v56, v208
	v_mul_f32_e32 v57, v57, v209
	v_lshlrev_b32_e32 v210, 16, v170
	v_and_b32_e32 v211, 0xffff0000, v170
	v_max_f32_e32 v210, 0x2b800000, v210
	v_max_f32_e32 v211, 0x2b800000, v211
	v_rcp_f32_e32 v210, v210
	v_rcp_f32_e32 v211, v211
	v_lshlrev_b32_e32 v170, 16, v156
	v_and_b32_e32 v156, 0xffff0000, v156
	v_mul_f32_e32 v210, v210, v170
	v_mul_f32_e32 v211, v211, v156
	v_mul_f32_e32 v50, v50, v210
	v_mul_f32_e32 v51, v51, v211
	v_lshlrev_b32_e32 v206, 16, v171
	v_and_b32_e32 v207, 0xffff0000, v171
	v_max_f32_e32 v206, 0x2b800000, v206
	v_max_f32_e32 v207, 0x2b800000, v207
	v_rcp_f32_e32 v206, v206
	v_rcp_f32_e32 v207, v207
	v_lshlrev_b32_e32 v171, 16, v157
	v_and_b32_e32 v157, 0xffff0000, v157
	v_mul_f32_e32 v206, v206, v171
	v_mul_f32_e32 v207, v207, v157
	v_mul_f32_e32 v52, v52, v206
	v_mul_f32_e32 v53, v53, v207
	s_waitcnt vmcnt(10)
	v_lshlrev_b32_e32 v206, 16, v176
	v_and_b32_e32 v207, 0xffff0000, v176
	v_max_f32_e32 v206, 0x2b800000, v206
	v_max_f32_e32 v207, 0x2b800000, v207
	v_rcp_f32_e32 v206, v206
	v_rcp_f32_e32 v207, v207
	v_lshlrev_b32_e32 v176, 16, v172
	v_and_b32_e32 v172, 0xffff0000, v172
	v_mul_f32_e32 v206, v206, v176
	v_mul_f32_e32 v207, v207, v172
	v_mul_f32_e32 v46, v46, v206
	v_mul_f32_e32 v47, v47, v207
	v_lshlrev_b32_e32 v208, 16, v177
	v_and_b32_e32 v209, 0xffff0000, v177
	v_max_f32_e32 v208, 0x2b800000, v208
	v_max_f32_e32 v209, 0x2b800000, v209
	v_rcp_f32_e32 v208, v208
	v_rcp_f32_e32 v209, v209
	v_lshlrev_b32_e32 v177, 16, v173
	v_and_b32_e32 v173, 0xffff0000, v173
	v_mul_f32_e32 v208, v208, v177
	v_mul_f32_e32 v209, v209, v173
	v_mul_f32_e32 v48, v48, v208
	v_mul_f32_e32 v49, v49, v209
	v_lshlrev_b32_e32 v210, 16, v178
	v_and_b32_e32 v211, 0xffff0000, v178
	v_max_f32_e32 v210, 0x2b800000, v210
	v_max_f32_e32 v211, 0x2b800000, v211
	v_rcp_f32_e32 v210, v210
	v_rcp_f32_e32 v211, v211
	v_lshlrev_b32_e32 v178, 16, v174
	v_and_b32_e32 v174, 0xffff0000, v174
	v_mul_f32_e32 v210, v210, v178
	v_mul_f32_e32 v211, v211, v174
	v_mul_f32_e32 v42, v42, v210
	v_mul_f32_e32 v43, v43, v211
	v_lshlrev_b32_e32 v206, 16, v179
	v_and_b32_e32 v207, 0xffff0000, v179
	v_max_f32_e32 v206, 0x2b800000, v206
	v_max_f32_e32 v207, 0x2b800000, v207
	v_rcp_f32_e32 v206, v206
	v_rcp_f32_e32 v207, v207
	v_lshlrev_b32_e32 v179, 16, v175
	v_and_b32_e32 v175, 0xffff0000, v175
	v_mul_f32_e32 v206, v206, v179
	v_mul_f32_e32 v207, v207, v175
	v_mul_f32_e32 v44, v44, v206
	v_mul_f32_e32 v45, v45, v207
	s_waitcnt vmcnt(8)
	v_lshlrev_b32_e32 v206, 16, v184
	v_and_b32_e32 v207, 0xffff0000, v184
	v_max_f32_e32 v206, 0x2b800000, v206
	v_max_f32_e32 v207, 0x2b800000, v207
	v_rcp_f32_e32 v206, v206
	v_rcp_f32_e32 v207, v207
	v_lshlrev_b32_e32 v184, 16, v180
	v_and_b32_e32 v180, 0xffff0000, v180
	v_mul_f32_e32 v206, v206, v184
	v_mul_f32_e32 v207, v207, v180
	v_mul_f32_e32 v38, v38, v206
	v_mul_f32_e32 v39, v39, v207
	v_lshlrev_b32_e32 v208, 16, v185
	v_and_b32_e32 v209, 0xffff0000, v185
	v_max_f32_e32 v208, 0x2b800000, v208
	v_max_f32_e32 v209, 0x2b800000, v209
	v_rcp_f32_e32 v208, v208
	v_rcp_f32_e32 v209, v209
	v_lshlrev_b32_e32 v185, 16, v181
	v_and_b32_e32 v181, 0xffff0000, v181
	v_mul_f32_e32 v208, v208, v185
	v_mul_f32_e32 v209, v209, v181
	v_mul_f32_e32 v40, v40, v208
	v_mul_f32_e32 v41, v41, v209
	v_lshlrev_b32_e32 v210, 16, v186
	v_and_b32_e32 v211, 0xffff0000, v186
	v_max_f32_e32 v210, 0x2b800000, v210
	v_max_f32_e32 v211, 0x2b800000, v211
	v_rcp_f32_e32 v210, v210
	v_rcp_f32_e32 v211, v211
	v_lshlrev_b32_e32 v186, 16, v182
	v_and_b32_e32 v182, 0xffff0000, v182
	v_mul_f32_e32 v210, v210, v186
	v_mul_f32_e32 v211, v211, v182
	v_mul_f32_e32 v34, v34, v210
	v_mul_f32_e32 v35, v35, v211
	v_lshlrev_b32_e32 v206, 16, v187
	v_and_b32_e32 v207, 0xffff0000, v187
	v_max_f32_e32 v206, 0x2b800000, v206
	v_max_f32_e32 v207, 0x2b800000, v207
	v_rcp_f32_e32 v206, v206
	v_rcp_f32_e32 v207, v207
	v_lshlrev_b32_e32 v187, 16, v183
	v_and_b32_e32 v183, 0xffff0000, v183
	v_mul_f32_e32 v206, v206, v187
	v_mul_f32_e32 v207, v207, v183
	v_mul_f32_e32 v36, v36, v206
	v_mul_f32_e32 v37, v37, v207
	s_waitcnt vmcnt(6)
; __device__ __forceinline__ u32x4 pack8(f32x4 a, f32x4 b) { u32x4 w; w.x = cvt_pk_bf16(a[0], a[1]); w.y = cvt_pk_bf16(a[2], a[3]); w.z = cvt_pk_bf16(b[0], b[1]); w.w = cvt_pk_bf16(b[2], b[3]); return w; }
; __device__ __forceinline__ void unpack8(u32x4 w, f32x4& a, f32x4& b) { a = (f32x4){bf_lo(w.x), bf_hi(w.x), bf_lo(w.y), bf_hi(w.y)}; b = (f32x4){bf_lo(w.z), bf_hi(w.z), bf_lo(w.w), bf_hi(w.w)}; }
;     __device__ __forceinline__ void operator()(const f32x4 (&acc)[2][2][4][2], const Unit& u, int wr, int wc, int fr, int fq) const {
;     ...
;                     } else if (MODE == EP_MERGE0 || MODE == EP_MERGE1) {
;                         f32x4 g0, g1; unpack8(*(const u32x4*)(aux + row * ldaux + col), g0, g1);
;                         v0 = g0 * v0; v1 = g1 * v1;
;                         if (MODE == EP_MERGE1) { f32x4 o0, o1; unpack8(*(const u32x4*)((const bf16_t*)O + row * ldc + col), o0, o1); v0 = v0 + o0; v1 = v1 + o1; }
;                         *(u32x4*)((bf16_t*)O + row * ldc + col) = pack8(v0, v1);
	v_lshlrev_b32_e32 v206, 16, v212
	v_and_b32_e32 v207, 0xffff0000, v212
	v_max_f32_e32 v206, 0x2b800000, v206
	v_max_f32_e32 v207, 0x2b800000, v207
	v_rcp_f32_e32 v206, v206
	v_rcp_f32_e32 v207, v207
	v_lshlrev_b32_e32 v212, 16, v188
	v_and_b32_e32 v188, 0xffff0000, v188
	v_mul_f32_e32 v206, v206, v212
	v_mul_f32_e32 v207, v207, v188
	v_mul_f32_e32 v30, v30, v206
	v_mul_f32_e32 v31, v31, v207
	v_lshlrev_b32_e32 v208, 16, v213
	v_and_b32_e32 v209, 0xffff0000, v213
	v_max_f32_e32 v208, 0x2b800000, v208
	v_max_f32_e32 v209, 0x2b800000, v209
	v_rcp_f32_e32 v208, v208
	v_rcp_f32_e32 v209, v209
	v_lshlrev_b32_e32 v213, 16, v189
	v_and_b32_e32 v189, 0xffff0000, v189
	v_mul_f32_e32 v208, v208, v213
	v_mul_f32_e32 v209, v209, v189
	v_mul_f32_e32 v32, v32, v208
	v_mul_f32_e32 v33, v33, v209
	v_lshlrev_b32_e32 v210, 16, v214
	v_and_b32_e32 v211, 0xffff0000, v214
	v_max_f32_e32 v210, 0x2b800000, v210
	v_max_f32_e32 v211, 0x2b800000, v211
	v_rcp_f32_e32 v210, v210
	v_rcp_f32_e32 v211, v211
	v_lshlrev_b32_e32 v214, 16, v190
	v_and_b32_e32 v190, 0xffff0000, v190
	v_mul_f32_e32 v210, v210, v214
	v_mul_f32_e32 v211, v211, v190
	v_mul_f32_e32 v26, v26, v210
	v_mul_f32_e32 v27, v27, v211
	v_lshlrev_b32_e32 v206, 16, v215
	v_and_b32_e32 v207, 0xffff0000, v215
	v_max_f32_e32 v206, 0x2b800000, v206
	v_max_f32_e32 v207, 0x2b800000, v207
	v_rcp_f32_e32 v206, v206
	v_rcp_f32_e32 v207, v207
	v_lshlrev_b32_e32 v215, 16, v191
	v_and_b32_e32 v191, 0xffff0000, v191
	v_mul_f32_e32 v206, v206, v215
	v_mul_f32_e32 v207, v207, v191
	v_mul_f32_e32 v28, v28, v206
	v_mul_f32_e32 v29, v29, v207
	s_waitcnt vmcnt(4)
	v_lshlrev_b32_e32 v206, 16, v220
	v_and_b32_e32 v207, 0xffff0000, v220
	v_max_f32_e32 v206, 0x2b800000, v206
	v_max_f32_e32 v207, 0x2b800000, v207
	v_rcp_f32_e32 v206, v206
	v_rcp_f32_e32 v207, v207
	v_lshlrev_b32_e32 v220, 16, v216
	v_and_b32_e32 v216, 0xffff0000, v216
	v_mul_f32_e32 v206, v206, v220
	v_mul_f32_e32 v207, v207, v216
	v_mul_f32_e32 v22, v22, v206
	v_mul_f32_e32 v23, v23, v207
	v_lshlrev_b32_e32 v208, 16, v221
	v_and_b32_e32 v209, 0xffff0000, v221
	v_max_f32_e32 v208, 0x2b800000, v208
	v_max_f32_e32 v209, 0x2b800000, v209
	v_rcp_f32_e32 v208, v208
	v_rcp_f32_e32 v209, v209
	v_lshlrev_b32_e32 v221, 16, v217
	v_and_b32_e32 v217, 0xffff0000, v217
	v_mul_f32_e32 v208, v208, v221
	v_mul_f32_e32 v209, v209, v217
	v_mul_f32_e32 v24, v24, v208
	v_mul_f32_e32 v25, v25, v209
	v_lshlrev_b32_e32 v210, 16, v222
	v_and_b32_e32 v211, 0xffff0000, v222
	v_max_f32_e32 v210, 0x2b800000, v210
	v_max_f32_e32 v211, 0x2b800000, v211
	v_rcp_f32_e32 v210, v210
	v_rcp_f32_e32 v211, v211
	v_lshlrev_b32_e32 v222, 16, v218
	v_and_b32_e32 v218, 0xffff0000, v218
	v_mul_f32_e32 v210, v210, v222
	v_mul_f32_e32 v211, v211, v218
	v_mul_f32_e32 v18, v18, v210
	v_mul_f32_e32 v19, v19, v211
	v_lshlrev_b32_e32 v206, 16, v223
	v_and_b32_e32 v207, 0xffff0000, v223
	v_max_f32_e32 v206, 0x2b800000, v206
	v_max_f32_e32 v207, 0x2b800000, v207
	v_rcp_f32_e32 v206, v206
	v_rcp_f32_e32 v207, v207
	v_lshlrev_b32_e32 v223, 16, v219
	v_and_b32_e32 v219, 0xffff0000, v219
	v_mul_f32_e32 v206, v206, v223
	v_mul_f32_e32 v207, v207, v219
	v_mul_f32_e32 v20, v20, v206
	v_mul_f32_e32 v21, v21, v207
	s_waitcnt vmcnt(2)
	v_lshlrev_b32_e32 v206, 16, v228
	v_and_b32_e32 v207, 0xffff0000, v228
	v_max_f32_e32 v206, 0x2b800000, v206
	v_max_f32_e32 v207, 0x2b800000, v207
	v_rcp_f32_e32 v206, v206
	v_rcp_f32_e32 v207, v207
	v_lshlrev_b32_e32 v228, 16, v224
	v_and_b32_e32 v224, 0xffff0000, v224
	v_mul_f32_e32 v206, v206, v228
	v_mul_f32_e32 v207, v207, v224
	v_mul_f32_e32 v14, v14, v206
	v_mul_f32_e32 v15, v15, v207
	v_lshlrev_b32_e32 v208, 16, v229
	v_and_b32_e32 v209, 0xffff0000, v229
	v_max_f32_e32 v208, 0x2b800000, v208
	v_max_f32_e32 v209, 0x2b800000, v209
	v_rcp_f32_e32 v208, v208
	v_rcp_f32_e32 v209, v209
	v_lshlrev_b32_e32 v229, 16, v225
	v_and_b32_e32 v225, 0xffff0000, v225
	v_mul_f32_e32 v208, v208, v229
	v_mul_f32_e32 v209, v209, v225
	v_mul_f32_e32 v16, v16, v208
	v_mul_f32_e32 v17, v17, v209
	v_lshlrev_b32_e32 v210, 16, v230
	v_and_b32_e32 v211, 0xffff0000, v230
	v_max_f32_e32 v210, 0x2b800000, v210
	v_max_f32_e32 v211, 0x2b800000, v211
	v_rcp_f32_e32 v210, v210
	v_rcp_f32_e32 v211, v211
	v_lshlrev_b32_e32 v230, 16, v226
	v_and_b32_e32 v226, 0xffff0000, v226
	v_mul_f32_e32 v210, v210, v230
	v_mul_f32_e32 v211, v211, v226
	v_mul_f32_e32 v10, v10, v210
	v_mul_f32_e32 v11, v11, v211
	v_lshlrev_b32_e32 v206, 16, v231
	v_and_b32_e32 v207, 0xffff0000, v231
	v_max_f32_e32 v206, 0x2b800000, v206
	v_max_f32_e32 v207, 0x2b800000, v207
	v_rcp_f32_e32 v206, v206
	v_rcp_f32_e32 v207, v207
	v_lshlrev_b32_e32 v231, 16, v227
	v_and_b32_e32 v227, 0xffff0000, v227
	v_mul_f32_e32 v206, v206, v231
	v_mul_f32_e32 v207, v207, v227
	v_mul_f32_e32 v12, v12, v206
	v_mul_f32_e32 v13, v13, v207
	s_waitcnt vmcnt(0)
	v_lshlrev_b32_e32 v206, 16, v236
	v_and_b32_e32 v207, 0xffff0000, v236
	v_max_f32_e32 v206, 0x2b800000, v206
	v_max_f32_e32 v207, 0x2b800000, v207
	v_rcp_f32_e32 v206, v206
	v_rcp_f32_e32 v207, v207
	v_lshlrev_b32_e32 v236, 16, v232
	v_and_b32_e32 v232, 0xffff0000, v232
	v_mul_f32_e32 v206, v206, v236
	v_mul_f32_e32 v207, v207, v232
	v_mul_f32_e32 v6, v6, v206
	v_mul_f32_e32 v7, v7, v207
	v_lshlrev_b32_e32 v208, 16, v237
	v_and_b32_e32 v209, 0xffff0000, v237
	v_max_f32_e32 v208, 0x2b800000, v208
	v_max_f32_e32 v209, 0x2b800000, v209
	v_rcp_f32_e32 v208, v208
	v_rcp_f32_e32 v209, v209
	v_lshlrev_b32_e32 v237, 16, v233
	v_and_b32_e32 v233, 0xffff0000, v233
	v_mul_f32_e32 v208, v208, v237
	v_mul_f32_e32 v209, v209, v233
	v_mul_f32_e32 v8, v8, v208
	v_mul_f32_e32 v9, v9, v209
	v_lshlrev_b32_e32 v210, 16, v238
	v_and_b32_e32 v211, 0xffff0000, v238
	v_max_f32_e32 v210, 0x2b800000, v210
	v_max_f32_e32 v211, 0x2b800000, v211
	v_rcp_f32_e32 v210, v210
	v_rcp_f32_e32 v211, v211
	v_lshlrev_b32_e32 v238, 16, v234
	v_and_b32_e32 v234, 0xffff0000, v234
	v_mul_f32_e32 v210, v210, v238
	v_mul_f32_e32 v211, v211, v234
	v_mul_f32_e32 v2, v2, v210
	v_mul_f32_e32 v3, v3, v211
	v_lshlrev_b32_e32 v206, 16, v239
	v_and_b32_e32 v207, 0xffff0000, v239
	v_max_f32_e32 v206, 0x2b800000, v206
	v_max_f32_e32 v207, 0x2b800000, v207
	v_rcp_f32_e32 v206, v206
	v_rcp_f32_e32 v207, v207
	v_lshlrev_b32_e32 v239, 16, v235
	v_and_b32_e32 v235, 0xffff0000, v235
	v_mul_f32_e32 v206, v206, v239
	v_mul_f32_e32 v207, v207, v235
	v_mul_f32_e32 v4, v4, v206
	v_mul_f32_e32 v5, v5, v207
	s_branch .Lmg_nohook
; __device__ __forceinline__ u32x4 pack8(f32x4 a, f32x4 b) { u32x4 w; w.x = cvt_pk_bf16(a[0], a[1]); w.y = cvt_pk_bf16(a[2], a[3]); w.z = cvt_pk_bf16(b[0], b[1]); w.w = cvt_pk_bf16(b[2], b[3]); return w; }
; __device__ __forceinline__ void unpack8(u32x4 w, f32x4& a, f32x4& b) { a = (f32x4){bf_lo(w.x), bf_hi(w.x), bf_lo(w.y), bf_hi(w.y)}; b = (f32x4){bf_lo(w.z), bf_hi(w.z), bf_lo(w.w), bf_hi(w.w)}; }
;     __device__ __forceinline__ void operator()(const f32x4 (&acc)[2][2][4][2], const Unit& u, int wr, int wc, int fr, int fq) const {
;     ...
;                     } else if (MODE == EP_MERGE0 || MODE == EP_MERGE1) {
;                         f32x4 g0, g1; unpack8(*(const u32x4*)(aux + row * ldaux + col), g0, g1);
;                         v0 = g0 * v0; v1 = g1 * v1;
;                         if (MODE == EP_MERGE1) { f32x4 o0, o1; unpack8(*(const u32x4*)((const bf16_t*)O + row * ldc + col), o0, o1); v0 = v0 + o0; v1 = v1 + o1; }
;                         *(u32x4*)((bf16_t*)O + row * ldc + col) = pack8(v0, v1);
.Lmg_rescale12:
	v_lshl_add_u32 v166, s42, 8, v148
	v_lshl_or_b32 v167, s41, 8, v152
	v_lshlrev_b32_e32 v167, 1, v167
	v_add_u32_e32 v167, 0x2800, v167
	v_add_u32_e32 v199, 0, v166
	v_mad_u32_u24 v205, v199, s81, v167
	v_add_u32_e32 v250, 0x1000, v205
	global_load_dwordx4 v[140:143], v205, s[68:69]
	global_load_dwordx4 v[144:147], v250, s[68:69]
	global_load_dwordx4 v[154:157], v205, s[68:69] offset:256
	global_load_dwordx4 v[168:171], v250, s[68:69] offset:256
	v_add_u32_e32 v199, 16, v166
	v_mad_u32_u24 v205, v199, s81, v167
	v_add_u32_e32 v250, 0x1000, v205
	global_load_dwordx4 v[172:175], v205, s[68:69]
	global_load_dwordx4 v[176:179], v250, s[68:69]
	global_load_dwordx4 v[180:183], v205, s[68:69] offset:256
	global_load_dwordx4 v[184:187], v250, s[68:69] offset:256
	v_add_u32_e32 v199, 32, v166
	v_mad_u32_u24 v205, v199, s81, v167
	v_add_u32_e32 v250, 0x1000, v205
	global_load_dwordx4 v[188:191], v205, s[68:69]
	global_load_dwordx4 v[212:215], v250, s[68:69]
	global_load_dwordx4 v[216:219], v205, s[68:69] offset:256
	global_load_dwordx4 v[220:223], v250, s[68:69] offset:256
	v_add_u32_e32 v199, 48, v166
	v_mad_u32_u24 v205, v199, s81, v167
	v_add_u32_e32 v250, 0x1000, v205
	global_load_dwordx4 v[224:227], v205, s[68:69]
	global_load_dwordx4 v[228:231], v250, s[68:69]
	global_load_dwordx4 v[232:235], v205, s[68:69] offset:256
	global_load_dwordx4 v[236:239], v250, s[68:69] offset:256
	s_waitcnt vmcnt(14)
	v_lshlrev_b32_e32 v206, 16, v144
	v_and_b32_e32 v207, 0xffff0000, v144
	v_max_f32_e32 v206, 0x2b800000, v206
	v_max_f32_e32 v207, 0x2b800000, v207
	v_rcp_f32_e32 v206, v206
	v_rcp_f32_e32 v207, v207
	v_lshlrev_b32_e32 v144, 16, v140
	v_and_b32_e32 v140, 0xffff0000, v140
	v_max_f32_e32 v144, 0x2b800000, v144
	v_max_f32_e32 v140, 0x2b800000, v140
	v_mul_f32_e32 v206, v206, v144
	v_mul_f32_e32 v207, v207, v140
	v_mul_f32_e32 v126, v126, v206
	v_mul_f32_e32 v127, v127, v207
	v_lshlrev_b32_e32 v208, 16, v145
	v_and_b32_e32 v209, 0xffff0000, v145
	v_max_f32_e32 v208, 0x2b800000, v208
	v_max_f32_e32 v209, 0x2b800000, v209
	v_rcp_f32_e32 v208, v208
	v_rcp_f32_e32 v209, v209
	v_lshlrev_b32_e32 v145, 16, v141
	v_and_b32_e32 v141, 0xffff0000, v141
	v_max_f32_e32 v145, 0x2b800000, v145
	v_max_f32_e32 v141, 0x2b800000, v141
	v_mul_f32_e32 v208, v208, v145
	v_mul_f32_e32 v209, v209, v141
	v_mul_f32_e32 v128, v128, v208
	v_mul_f32_e32 v129, v129, v209
	v_lshlrev_b32_e32 v210, 16, v146
	v_and_b32_e32 v211, 0xffff0000, v146
	v_max_f32_e32 v210, 0x2b800000, v210
	v_max_f32_e32 v211, 0x2b800000, v211
	v_rcp_f32_e32 v210, v210
	v_rcp_f32_e32 v211, v211
	v_lshlrev_b32_e32 v146, 16, v142
	v_and_b32_e32 v142, 0xffff0000, v142
	v_max_f32_e32 v146, 0x2b800000, v146
	v_max_f32_e32 v142, 0x2b800000, v142
	v_mul_f32_e32 v210, v210, v146
	v_mul_f32_e32 v211, v211, v142
	v_mul_f32_e32 v122, v122, v210
	v_mul_f32_e32 v123, v123, v211
	v_lshlrev_b32_e32 v206, 16, v147
	v_and_b32_e32 v207, 0xffff0000, v147
	v_max_f32_e32 v206, 0x2b800000, v206
	v_max_f32_e32 v207, 0x2b800000, v207
	v_rcp_f32_e32 v206, v206
	v_rcp_f32_e32 v207, v207
	v_lshlrev_b32_e32 v147, 16, v143
	v_and_b32_e32 v143, 0xffff0000, v143
	v_max_f32_e32 v147, 0x2b800000, v147
	v_max_f32_e32 v143, 0x2b800000, v143
	v_mul_f32_e32 v206, v206, v147
	v_mul_f32_e32 v207, v207, v143
	v_mul_f32_e32 v124, v124, v206
	v_mul_f32_e32 v125, v125, v207
	s_waitcnt vmcnt(12)
	v_lshlrev_b32_e32 v206, 16, v168
	v_and_b32_e32 v207, 0xffff0000, v168
	v_max_f32_e32 v206, 0x2b800000, v206
	v_max_f32_e32 v207, 0x2b800000, v207
	v_rcp_f32_e32 v206, v206
	v_rcp_f32_e32 v207, v207
	v_lshlrev_b32_e32 v168, 16, v154
	v_and_b32_e32 v154, 0xffff0000, v154
	v_max_f32_e32 v168, 0x2b800000, v168
	v_max_f32_e32 v154, 0x2b800000, v154
	v_mul_f32_e32 v206, v206, v168
	v_mul_f32_e32 v207, v207, v154
	v_mul_f32_e32 v118, v118, v206
	v_mul_f32_e32 v119, v119, v207
	v_lshlrev_b32_e32 v208, 16, v169
	v_and_b32_e32 v209, 0xffff0000, v169
	v_max_f32_e32 v208, 0x2b800000, v208
	v_max_f32_e32 v209, 0x2b800000, v209
	v_rcp_f32_e32 v208, v208
	v_rcp_f32_e32 v209, v209
	v_lshlrev_b32_e32 v169, 16, v155
	v_and_b32_e32 v155, 0xffff0000, v155
	v_max_f32_e32 v169, 0x2b800000, v169
	v_max_f32_e32 v155, 0x2b800000, v155
	v_mul_f32_e32 v208, v208, v169
	v_mul_f32_e32 v209, v209, v155
	v_mul_f32_e32 v120, v120, v208
	v_mul_f32_e32 v121, v121, v209
	v_lshlrev_b32_e32 v210, 16, v170
	v_and_b32_e32 v211, 0xffff0000, v170
	v_max_f32_e32 v210, 0x2b800000, v210
	v_max_f32_e32 v211, 0x2b800000, v211
	v_rcp_f32_e32 v210, v210
	v_rcp_f32_e32 v211, v211
	v_lshlrev_b32_e32 v170, 16, v156
	v_and_b32_e32 v156, 0xffff0000, v156
	v_max_f32_e32 v170, 0x2b800000, v170
	v_max_f32_e32 v156, 0x2b800000, v156
	v_mul_f32_e32 v210, v210, v170
	v_mul_f32_e32 v211, v211, v156
	v_mul_f32_e32 v114, v114, v210
	v_mul_f32_e32 v115, v115, v211
	v_lshlrev_b32_e32 v206, 16, v171
	v_and_b32_e32 v207, 0xffff0000, v171
	v_max_f32_e32 v206, 0x2b800000, v206
	v_max_f32_e32 v207, 0x2b800000, v207
	v_rcp_f32_e32 v206, v206
	v_rcp_f32_e32 v207, v207
	v_lshlrev_b32_e32 v171, 16, v157
	v_and_b32_e32 v157, 0xffff0000, v157
	v_max_f32_e32 v171, 0x2b800000, v171
	v_max_f32_e32 v157, 0x2b800000, v157
	v_mul_f32_e32 v206, v206, v171
	v_mul_f32_e32 v207, v207, v157
	v_mul_f32_e32 v116, v116, v206
	v_mul_f32_e32 v117, v117, v207
	v_add_u32_e32 v199, 128, v166
	v_mad_u32_u24 v205, v199, s81, v167
	v_add_u32_e32 v250, 0x1000, v205
	global_load_dwordx4 v[140:143], v205, s[68:69]
	global_load_dwordx4 v[144:147], v250, s[68:69]
	global_load_dwordx4 v[154:157], v205, s[68:69] offset:256
	global_load_dwordx4 v[168:171], v250, s[68:69] offset:256
	s_waitcnt vmcnt(14)
; __device__ __forceinline__ u32x4 pack8(f32x4 a, f32x4 b) { u32x4 w; w.x = cvt_pk_bf16(a[0], a[1]); w.y = cvt_pk_bf16(a[2], a[3]); w.z = cvt_pk_bf16(b[0], b[1]); w.w = cvt_pk_bf16(b[2], b[3]); return w; }
; __device__ __forceinline__ void unpack8(u32x4 w, f32x4& a, f32x4& b) { a = (f32x4){bf_lo(w.x), bf_hi(w.x), bf_lo(w.y), bf_hi(w.y)}; b = (f32x4){bf_lo(w.z), bf_hi(w.z), bf_lo(w.w), bf_hi(w.w)}; }
;     __device__ __forceinline__ void operator()(const f32x4 (&acc)[2][2][4][2], const Unit& u, int wr, int wc, int fr, int fq) const {
;     ...
;                     } else if (MODE == EP_MERGE0 || MODE == EP_MERGE1) {
;                         f32x4 g0, g1; unpack8(*(const u32x4*)(aux + row * ldaux + col), g0, g1);
;                         v0 = g0 * v0; v1 = g1 * v1;
;                         if (MODE == EP_MERGE1) { f32x4 o0, o1; unpack8(*(const u32x4*)((const bf16_t*)O + row * ldc + col), o0, o1); v0 = v0 + o0; v1 = v1 + o1; }
;                         *(u32x4*)((bf16_t*)O + row * ldc + col) = pack8(v0, v1);
	v_lshlrev_b32_e32 v206, 16, v176
	v_and_b32_e32 v207, 0xffff0000, v176
	v_max_f32_e32 v206, 0x2b800000, v206
	v_max_f32_e32 v207, 0x2b800000, v207
	v_rcp_f32_e32 v206, v206
	v_rcp_f32_e32 v207, v207
	v_lshlrev_b32_e32 v176, 16, v172
	v_and_b32_e32 v172, 0xffff0000, v172
	v_max_f32_e32 v176, 0x2b800000, v176
	v_max_f32_e32 v172, 0x2b800000, v172
	v_mul_f32_e32 v206, v206, v176
	v_mul_f32_e32 v207, v207, v172
	v_mul_f32_e32 v110, v110, v206
	v_mul_f32_e32 v111, v111, v207
	v_lshlrev_b32_e32 v208, 16, v177
	v_and_b32_e32 v209, 0xffff0000, v177
	v_max_f32_e32 v208, 0x2b800000, v208
	v_max_f32_e32 v209, 0x2b800000, v209
	v_rcp_f32_e32 v208, v208
	v_rcp_f32_e32 v209, v209
	v_lshlrev_b32_e32 v177, 16, v173
	v_and_b32_e32 v173, 0xffff0000, v173
	v_max_f32_e32 v177, 0x2b800000, v177
	v_max_f32_e32 v173, 0x2b800000, v173
	v_mul_f32_e32 v208, v208, v177
	v_mul_f32_e32 v209, v209, v173
	v_mul_f32_e32 v112, v112, v208
	v_mul_f32_e32 v113, v113, v209
	v_lshlrev_b32_e32 v210, 16, v178
	v_and_b32_e32 v211, 0xffff0000, v178
	v_max_f32_e32 v210, 0x2b800000, v210
	v_max_f32_e32 v211, 0x2b800000, v211
	v_rcp_f32_e32 v210, v210
	v_rcp_f32_e32 v211, v211
	v_lshlrev_b32_e32 v178, 16, v174
	v_and_b32_e32 v174, 0xffff0000, v174
	v_max_f32_e32 v178, 0x2b800000, v178
	v_max_f32_e32 v174, 0x2b800000, v174
	v_mul_f32_e32 v210, v210, v178
	v_mul_f32_e32 v211, v211, v174
	v_mul_f32_e32 v106, v106, v210
	v_mul_f32_e32 v107, v107, v211
	v_lshlrev_b32_e32 v206, 16, v179
	v_and_b32_e32 v207, 0xffff0000, v179
	v_max_f32_e32 v206, 0x2b800000, v206
	v_max_f32_e32 v207, 0x2b800000, v207
	v_rcp_f32_e32 v206, v206
	v_rcp_f32_e32 v207, v207
	v_lshlrev_b32_e32 v179, 16, v175
	v_and_b32_e32 v175, 0xffff0000, v175
	v_max_f32_e32 v179, 0x2b800000, v179
	v_max_f32_e32 v175, 0x2b800000, v175
	v_mul_f32_e32 v206, v206, v179
	v_mul_f32_e32 v207, v207, v175
	v_mul_f32_e32 v108, v108, v206
	v_mul_f32_e32 v109, v109, v207
	s_waitcnt vmcnt(12)
	v_lshlrev_b32_e32 v206, 16, v184
	v_and_b32_e32 v207, 0xffff0000, v184
	v_max_f32_e32 v206, 0x2b800000, v206
	v_max_f32_e32 v207, 0x2b800000, v207
	v_rcp_f32_e32 v206, v206
	v_rcp_f32_e32 v207, v207
	v_lshlrev_b32_e32 v184, 16, v180
	v_and_b32_e32 v180, 0xffff0000, v180
	v_max_f32_e32 v184, 0x2b800000, v184
	v_max_f32_e32 v180, 0x2b800000, v180
	v_mul_f32_e32 v206, v206, v184
	v_mul_f32_e32 v207, v207, v180
	v_mul_f32_e32 v102, v102, v206
	v_mul_f32_e32 v103, v103, v207
	v_lshlrev_b32_e32 v208, 16, v185
	v_and_b32_e32 v209, 0xffff0000, v185
	v_max_f32_e32 v208, 0x2b800000, v208
	v_max_f32_e32 v209, 0x2b800000, v209
	v_rcp_f32_e32 v208, v208
	v_rcp_f32_e32 v209, v209
	v_lshlrev_b32_e32 v185, 16, v181
	v_and_b32_e32 v181, 0xffff0000, v181
	v_max_f32_e32 v185, 0x2b800000, v185
	v_max_f32_e32 v181, 0x2b800000, v181
	v_mul_f32_e32 v208, v208, v185
	v_mul_f32_e32 v209, v209, v181
	v_mul_f32_e32 v104, v104, v208
	v_mul_f32_e32 v105, v105, v209
	v_lshlrev_b32_e32 v210, 16, v186
	v_and_b32_e32 v211, 0xffff0000, v186
	v_max_f32_e32 v210, 0x2b800000, v210
	v_max_f32_e32 v211, 0x2b800000, v211
	v_rcp_f32_e32 v210, v210
	v_rcp_f32_e32 v211, v211
	v_lshlrev_b32_e32 v186, 16, v182
	v_and_b32_e32 v182, 0xffff0000, v182
	v_max_f32_e32 v186, 0x2b800000, v186
	v_max_f32_e32 v182, 0x2b800000, v182
	v_mul_f32_e32 v210, v210, v186
	v_mul_f32_e32 v211, v211, v182
	v_mul_f32_e32 v98, v98, v210
	v_mul_f32_e32 v99, v99, v211
	v_lshlrev_b32_e32 v206, 16, v187
	v_and_b32_e32 v207, 0xffff0000, v187
	v_max_f32_e32 v206, 0x2b800000, v206
	v_max_f32_e32 v207, 0x2b800000, v207
	v_rcp_f32_e32 v206, v206
	v_rcp_f32_e32 v207, v207
	v_lshlrev_b32_e32 v187, 16, v183
	v_and_b32_e32 v183, 0xffff0000, v183
	v_max_f32_e32 v187, 0x2b800000, v187
	v_max_f32_e32 v183, 0x2b800000, v183
	v_mul_f32_e32 v206, v206, v187
	v_mul_f32_e32 v207, v207, v183
	v_mul_f32_e32 v100, v100, v206
	v_mul_f32_e32 v101, v101, v207
	v_add_u32_e32 v199, 144, v166
	v_mad_u32_u24 v205, v199, s81, v167
	v_add_u32_e32 v250, 0x1000, v205
	global_load_dwordx4 v[172:175], v205, s[68:69]
	global_load_dwordx4 v[176:179], v250, s[68:69]
	global_load_dwordx4 v[180:183], v205, s[68:69] offset:256
	global_load_dwordx4 v[184:187], v250, s[68:69] offset:256
	s_waitcnt vmcnt(14)
	v_lshlrev_b32_e32 v206, 16, v212
	v_and_b32_e32 v207, 0xffff0000, v212
	v_max_f32_e32 v206, 0x2b800000, v206
	v_max_f32_e32 v207, 0x2b800000, v207
	v_rcp_f32_e32 v206, v206
	v_rcp_f32_e32 v207, v207
	v_lshlrev_b32_e32 v212, 16, v188
	v_and_b32_e32 v188, 0xffff0000, v188
	v_max_f32_e32 v212, 0x2b800000, v212
	v_max_f32_e32 v188, 0x2b800000, v188
	v_mul_f32_e32 v206, v206, v212
	v_mul_f32_e32 v207, v207, v188
	v_mul_f32_e32 v94, v94, v206
	v_mul_f32_e32 v95, v95, v207
	v_lshlrev_b32_e32 v208, 16, v213
	v_and_b32_e32 v209, 0xffff0000, v213
	v_max_f32_e32 v208, 0x2b800000, v208
	v_max_f32_e32 v209, 0x2b800000, v209
	v_rcp_f32_e32 v208, v208
	v_rcp_f32_e32 v209, v209
	v_lshlrev_b32_e32 v213, 16, v189
	v_and_b32_e32 v189, 0xffff0000, v189
	v_max_f32_e32 v213, 0x2b800000, v213
	v_max_f32_e32 v189, 0x2b800000, v189
	v_mul_f32_e32 v208, v208, v213
	v_mul_f32_e32 v209, v209, v189
	v_mul_f32_e32 v96, v96, v208
	v_mul_f32_e32 v97, v97, v209
	v_lshlrev_b32_e32 v210, 16, v214
	v_and_b32_e32 v211, 0xffff0000, v214
	v_max_f32_e32 v210, 0x2b800000, v210
	v_max_f32_e32 v211, 0x2b800000, v211
	v_rcp_f32_e32 v210, v210
	v_rcp_f32_e32 v211, v211
	v_lshlrev_b32_e32 v214, 16, v190
	v_and_b32_e32 v190, 0xffff0000, v190
	v_max_f32_e32 v214, 0x2b800000, v214
	v_max_f32_e32 v190, 0x2b800000, v190
	v_mul_f32_e32 v210, v210, v214
	v_mul_f32_e32 v211, v211, v190
	v_mul_f32_e32 v90, v90, v210
	v_mul_f32_e32 v91, v91, v211
	v_lshlrev_b32_e32 v206, 16, v215
	v_and_b32_e32 v207, 0xffff0000, v215
	v_max_f32_e32 v206, 0x2b800000, v206
	v_max_f32_e32 v207, 0x2b800000, v207
	v_rcp_f32_e32 v206, v206
	v_rcp_f32_e32 v207, v207
	v_lshlrev_b32_e32 v215, 16, v191
	v_and_b32_e32 v191, 0xffff0000, v191
	v_max_f32_e32 v215, 0x2b800000, v215
	v_max_f32_e32 v191, 0x2b800000, v191
	v_mul_f32_e32 v206, v206, v215
	v_mul_f32_e32 v207, v207, v191
	v_mul_f32_e32 v92, v92, v206
	v_mul_f32_e32 v93, v93, v207
	s_waitcnt vmcnt(12)
; __device__ __forceinline__ u32x4 pack8(f32x4 a, f32x4 b) { u32x4 w; w.x = cvt_pk_bf16(a[0], a[1]); w.y = cvt_pk_bf16(a[2], a[3]); w.z = cvt_pk_bf16(b[0], b[1]); w.w = cvt_pk_bf16(b[2], b[3]); return w; }
; __device__ __forceinline__ void unpack8(u32x4 w, f32x4& a, f32x4& b) { a = (f32x4){bf_lo(w.x), bf_hi(w.x), bf_lo(w.y), bf_hi(w.y)}; b = (f32x4){bf_lo(w.z), bf_hi(w.z), bf_lo(w.w), bf_hi(w.w)}; }
;     __device__ __forceinline__ void operator()(const f32x4 (&acc)[2][2][4][2], const Unit& u, int wr, int wc, int fr, int fq) const {
;     ...
;                     } else if (MODE == EP_MERGE0 || MODE == EP_MERGE1) {
;                         f32x4 g0, g1; unpack8(*(const u32x4*)(aux + row * ldaux + col), g0, g1);
;                         v0 = g0 * v0; v1 = g1 * v1;
;                         if (MODE == EP_MERGE1) { f32x4 o0, o1; unpack8(*(const u32x4*)((const bf16_t*)O + row * ldc + col), o0, o1); v0 = v0 + o0; v1 = v1 + o1; }
;                         *(u32x4*)((bf16_t*)O + row * ldc + col) = pack8(v0, v1);
	v_lshlrev_b32_e32 v206, 16, v220
	v_and_b32_e32 v207, 0xffff0000, v220
	v_max_f32_e32 v206, 0x2b800000, v206
	v_max_f32_e32 v207, 0x2b800000, v207
	v_rcp_f32_e32 v206, v206
	v_rcp_f32_e32 v207, v207
	v_lshlrev_b32_e32 v220, 16, v216
	v_and_b32_e32 v216, 0xffff0000, v216
	v_max_f32_e32 v220, 0x2b800000, v220
	v_max_f32_e32 v216, 0x2b800000, v216
	v_mul_f32_e32 v206, v206, v220
	v_mul_f32_e32 v207, v207, v216
	v_mul_f32_e32 v86, v86, v206
	v_mul_f32_e32 v87, v87, v207
	v_lshlrev_b32_e32 v208, 16, v221
	v_and_b32_e32 v209, 0xffff0000, v221
	v_max_f32_e32 v208, 0x2b800000, v208
	v_max_f32_e32 v209, 0x2b800000, v209
	v_rcp_f32_e32 v208, v208
	v_rcp_f32_e32 v209, v209
	v_lshlrev_b32_e32 v221, 16, v217
	v_and_b32_e32 v217, 0xffff0000, v217
	v_max_f32_e32 v221, 0x2b800000, v221
	v_max_f32_e32 v217, 0x2b800000, v217
	v_mul_f32_e32 v208, v208, v221
	v_mul_f32_e32 v209, v209, v217
	v_mul_f32_e32 v88, v88, v208
	v_mul_f32_e32 v89, v89, v209
	v_lshlrev_b32_e32 v210, 16, v222
	v_and_b32_e32 v211, 0xffff0000, v222
	v_max_f32_e32 v210, 0x2b800000, v210
	v_max_f32_e32 v211, 0x2b800000, v211
	v_rcp_f32_e32 v210, v210
	v_rcp_f32_e32 v211, v211
	v_lshlrev_b32_e32 v222, 16, v218
	v_and_b32_e32 v218, 0xffff0000, v218
	v_max_f32_e32 v222, 0x2b800000, v222
	v_max_f32_e32 v218, 0x2b800000, v218
	v_mul_f32_e32 v210, v210, v222
	v_mul_f32_e32 v211, v211, v218
	v_mul_f32_e32 v82, v82, v210
	v_mul_f32_e32 v83, v83, v211
	v_lshlrev_b32_e32 v206, 16, v223
	v_and_b32_e32 v207, 0xffff0000, v223
	v_max_f32_e32 v206, 0x2b800000, v206
	v_max_f32_e32 v207, 0x2b800000, v207
	v_rcp_f32_e32 v206, v206
	v_rcp_f32_e32 v207, v207
	v_lshlrev_b32_e32 v223, 16, v219
	v_and_b32_e32 v219, 0xffff0000, v219
	v_max_f32_e32 v223, 0x2b800000, v223
	v_max_f32_e32 v219, 0x2b800000, v219
	v_mul_f32_e32 v206, v206, v223
	v_mul_f32_e32 v207, v207, v219
	v_mul_f32_e32 v84, v84, v206
	v_mul_f32_e32 v85, v85, v207
	v_add_u32_e32 v199, 160, v166
	v_mad_u32_u24 v205, v199, s81, v167
	v_add_u32_e32 v250, 0x1000, v205
	global_load_dwordx4 v[188:191], v205, s[68:69]
	global_load_dwordx4 v[212:215], v250, s[68:69]
	global_load_dwordx4 v[216:219], v205, s[68:69] offset:256
	global_load_dwordx4 v[220:223], v250, s[68:69] offset:256
	s_waitcnt vmcnt(14)
	v_lshlrev_b32_e32 v206, 16, v228
	v_and_b32_e32 v207, 0xffff0000, v228
	v_max_f32_e32 v206, 0x2b800000, v206
	v_max_f32_e32 v207, 0x2b800000, v207
	v_rcp_f32_e32 v206, v206
	v_rcp_f32_e32 v207, v207
	v_lshlrev_b32_e32 v228, 16, v224
	v_and_b32_e32 v224, 0xffff0000, v224
	v_max_f32_e32 v228, 0x2b800000, v228
	v_max_f32_e32 v224, 0x2b800000, v224
	v_mul_f32_e32 v206, v206, v228
	v_mul_f32_e32 v207, v207, v224
	v_mul_f32_e32 v78, v78, v206
	v_mul_f32_e32 v79, v79, v207
	v_lshlrev_b32_e32 v208, 16, v229
	v_and_b32_e32 v209, 0xffff0000, v229
	v_max_f32_e32 v208, 0x2b800000, v208
	v_max_f32_e32 v209, 0x2b800000, v209
	v_rcp_f32_e32 v208, v208
	v_rcp_f32_e32 v209, v209
	v_lshlrev_b32_e32 v229, 16, v225
	v_and_b32_e32 v225, 0xffff0000, v225
	v_max_f32_e32 v229, 0x2b800000, v229
	v_max_f32_e32 v225, 0x2b800000, v225
	v_mul_f32_e32 v208, v208, v229
	v_mul_f32_e32 v209, v209, v225
	v_mul_f32_e32 v80, v80, v208
	v_mul_f32_e32 v81, v81, v209
	v_lshlrev_b32_e32 v210, 16, v230
	v_and_b32_e32 v211, 0xffff0000, v230
	v_max_f32_e32 v210, 0x2b800000, v210
	v_max_f32_e32 v211, 0x2b800000, v211
	v_rcp_f32_e32 v210, v210
	v_rcp_f32_e32 v211, v211
	v_lshlrev_b32_e32 v230, 16, v226
	v_and_b32_e32 v226, 0xffff0000, v226
	v_max_f32_e32 v230, 0x2b800000, v230
	v_max_f32_e32 v226, 0x2b800000, v226
	v_mul_f32_e32 v210, v210, v230
	v_mul_f32_e32 v211, v211, v226
	v_mul_f32_e32 v74, v74, v210
	v_mul_f32_e32 v75, v75, v211
	v_lshlrev_b32_e32 v206, 16, v231
	v_and_b32_e32 v207, 0xffff0000, v231
	v_max_f32_e32 v206, 0x2b800000, v206
	v_max_f32_e32 v207, 0x2b800000, v207
	v_rcp_f32_e32 v206, v206
	v_rcp_f32_e32 v207, v207
	v_lshlrev_b32_e32 v231, 16, v227
	v_and_b32_e32 v227, 0xffff0000, v227
	v_max_f32_e32 v231, 0x2b800000, v231
	v_max_f32_e32 v227, 0x2b800000, v227
	v_mul_f32_e32 v206, v206, v231
	v_mul_f32_e32 v207, v207, v227
	v_mul_f32_e32 v76, v76, v206
	v_mul_f32_e32 v77, v77, v207
	s_waitcnt vmcnt(12)
	v_lshlrev_b32_e32 v206, 16, v236
	v_and_b32_e32 v207, 0xffff0000, v236
	v_max_f32_e32 v206, 0x2b800000, v206
	v_max_f32_e32 v207, 0x2b800000, v207
	v_rcp_f32_e32 v206, v206
	v_rcp_f32_e32 v207, v207
	v_lshlrev_b32_e32 v236, 16, v232
	v_and_b32_e32 v232, 0xffff0000, v232
	v_max_f32_e32 v236, 0x2b800000, v236
	v_max_f32_e32 v232, 0x2b800000, v232
	v_mul_f32_e32 v206, v206, v236
	v_mul_f32_e32 v207, v207, v232
	v_mul_f32_e32 v70, v70, v206
	v_mul_f32_e32 v71, v71, v207
	v_lshlrev_b32_e32 v208, 16, v237
	v_and_b32_e32 v209, 0xffff0000, v237
	v_max_f32_e32 v208, 0x2b800000, v208
	v_max_f32_e32 v209, 0x2b800000, v209
	v_rcp_f32_e32 v208, v208
	v_rcp_f32_e32 v209, v209
	v_lshlrev_b32_e32 v237, 16, v233
	v_and_b32_e32 v233, 0xffff0000, v233
	v_max_f32_e32 v237, 0x2b800000, v237
	v_max_f32_e32 v233, 0x2b800000, v233
	v_mul_f32_e32 v208, v208, v237
	v_mul_f32_e32 v209, v209, v233
	v_mul_f32_e32 v72, v72, v208
	v_mul_f32_e32 v73, v73, v209
	v_lshlrev_b32_e32 v210, 16, v238
	v_and_b32_e32 v211, 0xffff0000, v238
	v_max_f32_e32 v210, 0x2b800000, v210
	v_max_f32_e32 v211, 0x2b800000, v211
	v_rcp_f32_e32 v210, v210
	v_rcp_f32_e32 v211, v211
	v_lshlrev_b32_e32 v238, 16, v234
	v_and_b32_e32 v234, 0xffff0000, v234
	v_max_f32_e32 v238, 0x2b800000, v238
	v_max_f32_e32 v234, 0x2b800000, v234
	v_mul_f32_e32 v210, v210, v238
	v_mul_f32_e32 v211, v211, v234
	v_mul_f32_e32 v66, v66, v210
	v_mul_f32_e32 v67, v67, v211
	v_lshlrev_b32_e32 v206, 16, v239
	v_and_b32_e32 v207, 0xffff0000, v239
	v_max_f32_e32 v206, 0x2b800000, v206
	v_max_f32_e32 v207, 0x2b800000, v207
	v_rcp_f32_e32 v206, v206
	v_rcp_f32_e32 v207, v207
	v_lshlrev_b32_e32 v239, 16, v235
	v_and_b32_e32 v235, 0xffff0000, v235
	v_max_f32_e32 v239, 0x2b800000, v239
	v_max_f32_e32 v235, 0x2b800000, v235
	v_mul_f32_e32 v206, v206, v239
	v_mul_f32_e32 v207, v207, v235
	v_mul_f32_e32 v68, v68, v206
	v_mul_f32_e32 v69, v69, v207
	v_add_u32_e32 v199, 176, v166
	v_mad_u32_u24 v205, v199, s81, v167
	v_add_u32_e32 v250, 0x1000, v205
	global_load_dwordx4 v[224:227], v205, s[68:69]
	global_load_dwordx4 v[228:231], v250, s[68:69]
	global_load_dwordx4 v[232:235], v205, s[68:69] offset:256
	global_load_dwordx4 v[236:239], v250, s[68:69] offset:256
	s_waitcnt vmcnt(14)
; __device__ __forceinline__ u32x4 pack8(f32x4 a, f32x4 b) { u32x4 w; w.x = cvt_pk_bf16(a[0], a[1]); w.y = cvt_pk_bf16(a[2], a[3]); w.z = cvt_pk_bf16(b[0], b[1]); w.w = cvt_pk_bf16(b[2], b[3]); return w; }
; __device__ __forceinline__ void unpack8(u32x4 w, f32x4& a, f32x4& b) { a = (f32x4){bf_lo(w.x), bf_hi(w.x), bf_lo(w.y), bf_hi(w.y)}; b = (f32x4){bf_lo(w.z), bf_hi(w.z), bf_lo(w.w), bf_hi(w.w)}; }
;     __device__ __forceinline__ void operator()(const f32x4 (&acc)[2][2][4][2], const Unit& u, int wr, int wc, int fr, int fq) const {
;     ...
;                     } else if (MODE == EP_MERGE0 || MODE == EP_MERGE1) {
;                         f32x4 g0, g1; unpack8(*(const u32x4*)(aux + row * ldaux + col), g0, g1);
;                         v0 = g0 * v0; v1 = g1 * v1;
;                         if (MODE == EP_MERGE1) { f32x4 o0, o1; unpack8(*(const u32x4*)((const bf16_t*)O + row * ldc + col), o0, o1); v0 = v0 + o0; v1 = v1 + o1; }
;                         *(u32x4*)((bf16_t*)O + row * ldc + col) = pack8(v0, v1);
	v_lshlrev_b32_e32 v206, 16, v144
	v_and_b32_e32 v207, 0xffff0000, v144
	v_max_f32_e32 v206, 0x2b800000, v206
	v_max_f32_e32 v207, 0x2b800000, v207
	v_rcp_f32_e32 v206, v206
	v_rcp_f32_e32 v207, v207
	v_lshlrev_b32_e32 v144, 16, v140
	v_and_b32_e32 v140, 0xffff0000, v140
	v_max_f32_e32 v144, 0x2b800000, v144
	v_max_f32_e32 v140, 0x2b800000, v140
	v_mul_f32_e32 v206, v206, v144
	v_mul_f32_e32 v207, v207, v140
	v_mul_f32_e32 v62, v62, v206
	v_mul_f32_e32 v63, v63, v207
	v_lshlrev_b32_e32 v208, 16, v145
	v_and_b32_e32 v209, 0xffff0000, v145
	v_max_f32_e32 v208, 0x2b800000, v208
	v_max_f32_e32 v209, 0x2b800000, v209
	v_rcp_f32_e32 v208, v208
	v_rcp_f32_e32 v209, v209
	v_lshlrev_b32_e32 v145, 16, v141
	v_and_b32_e32 v141, 0xffff0000, v141
	v_max_f32_e32 v145, 0x2b800000, v145
	v_max_f32_e32 v141, 0x2b800000, v141
	v_mul_f32_e32 v208, v208, v145
	v_mul_f32_e32 v209, v209, v141
	v_mul_f32_e32 v64, v64, v208
	v_mul_f32_e32 v65, v65, v209
	v_lshlrev_b32_e32 v210, 16, v146
	v_and_b32_e32 v211, 0xffff0000, v146
	v_max_f32_e32 v210, 0x2b800000, v210
	v_max_f32_e32 v211, 0x2b800000, v211
	v_rcp_f32_e32 v210, v210
	v_rcp_f32_e32 v211, v211
	v_lshlrev_b32_e32 v146, 16, v142
	v_and_b32_e32 v142, 0xffff0000, v142
	v_max_f32_e32 v146, 0x2b800000, v146
	v_max_f32_e32 v142, 0x2b800000, v142
	v_mul_f32_e32 v210, v210, v146
	v_mul_f32_e32 v211, v211, v142
	v_mul_f32_e32 v58, v58, v210
	v_mul_f32_e32 v59, v59, v211
	v_lshlrev_b32_e32 v206, 16, v147
	v_and_b32_e32 v207, 0xffff0000, v147
	v_max_f32_e32 v206, 0x2b800000, v206
	v_max_f32_e32 v207, 0x2b800000, v207
	v_rcp_f32_e32 v206, v206
	v_rcp_f32_e32 v207, v207
	v_lshlrev_b32_e32 v147, 16, v143
	v_and_b32_e32 v143, 0xffff0000, v143
	v_max_f32_e32 v147, 0x2b800000, v147
	v_max_f32_e32 v143, 0x2b800000, v143
	v_mul_f32_e32 v206, v206, v147
	v_mul_f32_e32 v207, v207, v143
	v_mul_f32_e32 v60, v60, v206
	v_mul_f32_e32 v61, v61, v207
	s_waitcnt vmcnt(12)
	v_lshlrev_b32_e32 v206, 16, v168
	v_and_b32_e32 v207, 0xffff0000, v168
	v_max_f32_e32 v206, 0x2b800000, v206
	v_max_f32_e32 v207, 0x2b800000, v207
	v_rcp_f32_e32 v206, v206
	v_rcp_f32_e32 v207, v207
	v_lshlrev_b32_e32 v168, 16, v154
	v_and_b32_e32 v154, 0xffff0000, v154
	v_max_f32_e32 v168, 0x2b800000, v168
	v_max_f32_e32 v154, 0x2b800000, v154
	v_mul_f32_e32 v206, v206, v168
	v_mul_f32_e32 v207, v207, v154
	v_mul_f32_e32 v54, v54, v206
	v_mul_f32_e32 v55, v55, v207
	v_lshlrev_b32_e32 v208, 16, v169
	v_and_b32_e32 v209, 0xffff0000, v169
	v_max_f32_e32 v208, 0x2b800000, v208
	v_max_f32_e32 v209, 0x2b800000, v209
	v_rcp_f32_e32 v208, v208
	v_rcp_f32_e32 v209, v209
	v_lshlrev_b32_e32 v169, 16, v155
	v_and_b32_e32 v155, 0xffff0000, v155
	v_max_f32_e32 v169, 0x2b800000, v169
	v_max_f32_e32 v155, 0x2b800000, v155
	v_mul_f32_e32 v208, v208, v169
	v_mul_f32_e32 v209, v209, v155
	v_mul_f32_e32 v56, v56, v208
	v_mul_f32_e32 v57, v57, v209
	v_lshlrev_b32_e32 v210, 16, v170
	v_and_b32_e32 v211, 0xffff0000, v170
	v_max_f32_e32 v210, 0x2b800000, v210
	v_max_f32_e32 v211, 0x2b800000, v211
	v_rcp_f32_e32 v210, v210
	v_rcp_f32_e32 v211, v211
	v_lshlrev_b32_e32 v170, 16, v156
	v_and_b32_e32 v156, 0xffff0000, v156
	v_max_f32_e32 v170, 0x2b800000, v170
	v_max_f32_e32 v156, 0x2b800000, v156
	v_mul_f32_e32 v210, v210, v170
	v_mul_f32_e32 v211, v211, v156
	v_mul_f32_e32 v50, v50, v210
	v_mul_f32_e32 v51, v51, v211
	v_lshlrev_b32_e32 v206, 16, v171
	v_and_b32_e32 v207, 0xffff0000, v171
	v_max_f32_e32 v206, 0x2b800000, v206
	v_max_f32_e32 v207, 0x2b800000, v207
	v_rcp_f32_e32 v206, v206
	v_rcp_f32_e32 v207, v207
	v_lshlrev_b32_e32 v171, 16, v157
	v_and_b32_e32 v157, 0xffff0000, v157
	v_max_f32_e32 v171, 0x2b800000, v171
	v_max_f32_e32 v157, 0x2b800000, v157
	v_mul_f32_e32 v206, v206, v171
	v_mul_f32_e32 v207, v207, v157
	v_mul_f32_e32 v52, v52, v206
	v_mul_f32_e32 v53, v53, v207
	s_waitcnt vmcnt(10)
	v_lshlrev_b32_e32 v206, 16, v176
	v_and_b32_e32 v207, 0xffff0000, v176
	v_max_f32_e32 v206, 0x2b800000, v206
	v_max_f32_e32 v207, 0x2b800000, v207
	v_rcp_f32_e32 v206, v206
	v_rcp_f32_e32 v207, v207
	v_lshlrev_b32_e32 v176, 16, v172
	v_and_b32_e32 v172, 0xffff0000, v172
	v_max_f32_e32 v176, 0x2b800000, v176
	v_max_f32_e32 v172, 0x2b800000, v172
	v_mul_f32_e32 v206, v206, v176
	v_mul_f32_e32 v207, v207, v172
	v_mul_f32_e32 v46, v46, v206
	v_mul_f32_e32 v47, v47, v207
	v_lshlrev_b32_e32 v208, 16, v177
	v_and_b32_e32 v209, 0xffff0000, v177
	v_max_f32_e32 v208, 0x2b800000, v208
	v_max_f32_e32 v209, 0x2b800000, v209
	v_rcp_f32_e32 v208, v208
	v_rcp_f32_e32 v209, v209
	v_lshlrev_b32_e32 v177, 16, v173
	v_and_b32_e32 v173, 0xffff0000, v173
	v_max_f32_e32 v177, 0x2b800000, v177
	v_max_f32_e32 v173, 0x2b800000, v173
	v_mul_f32_e32 v208, v208, v177
	v_mul_f32_e32 v209, v209, v173
	v_mul_f32_e32 v48, v48, v208
	v_mul_f32_e32 v49, v49, v209
	v_lshlrev_b32_e32 v210, 16, v178
	v_and_b32_e32 v211, 0xffff0000, v178
	v_max_f32_e32 v210, 0x2b800000, v210
	v_max_f32_e32 v211, 0x2b800000, v211
	v_rcp_f32_e32 v210, v210
	v_rcp_f32_e32 v211, v211
	v_lshlrev_b32_e32 v178, 16, v174
	v_and_b32_e32 v174, 0xffff0000, v174
	v_max_f32_e32 v178, 0x2b800000, v178
	v_max_f32_e32 v174, 0x2b800000, v174
	v_mul_f32_e32 v210, v210, v178
	v_mul_f32_e32 v211, v211, v174
	v_mul_f32_e32 v42, v42, v210
	v_mul_f32_e32 v43, v43, v211
	v_lshlrev_b32_e32 v206, 16, v179
	v_and_b32_e32 v207, 0xffff0000, v179
	v_max_f32_e32 v206, 0x2b800000, v206
	v_max_f32_e32 v207, 0x2b800000, v207
	v_rcp_f32_e32 v206, v206
	v_rcp_f32_e32 v207, v207
	v_lshlrev_b32_e32 v179, 16, v175
	v_and_b32_e32 v175, 0xffff0000, v175
	v_max_f32_e32 v179, 0x2b800000, v179
	v_max_f32_e32 v175, 0x2b800000, v175
	v_mul_f32_e32 v206, v206, v179
	v_mul_f32_e32 v207, v207, v175
	v_mul_f32_e32 v44, v44, v206
	v_mul_f32_e32 v45, v45, v207
	s_waitcnt vmcnt(8)
; __device__ __forceinline__ u32x4 pack8(f32x4 a, f32x4 b) { u32x4 w; w.x = cvt_pk_bf16(a[0], a[1]); w.y = cvt_pk_bf16(a[2], a[3]); w.z = cvt_pk_bf16(b[0], b[1]); w.w = cvt_pk_bf16(b[2], b[3]); return w; }
; __device__ __forceinline__ void unpack8(u32x4 w, f32x4& a, f32x4& b) { a = (f32x4){bf_lo(w.x), bf_hi(w.x), bf_lo(w.y), bf_hi(w.y)}; b = (f32x4){bf_lo(w.z), bf_hi(w.z), bf_lo(w.w), bf_hi(w.w)}; }
;     __device__ __forceinline__ void operator()(const f32x4 (&acc)[2][2][4][2], const Unit& u, int wr, int wc, int fr, int fq) const {
;     ...
;                     } else if (MODE == EP_MERGE0 || MODE == EP_MERGE1) {
;                         f32x4 g0, g1; unpack8(*(const u32x4*)(aux + row * ldaux + col), g0, g1);
;                         v0 = g0 * v0; v1 = g1 * v1;
;                         if (MODE == EP_MERGE1) { f32x4 o0, o1; unpack8(*(const u32x4*)((const bf16_t*)O + row * ldc + col), o0, o1); v0 = v0 + o0; v1 = v1 + o1; }
;                         *(u32x4*)((bf16_t*)O + row * ldc + col) = pack8(v0, v1);
	v_lshlrev_b32_e32 v206, 16, v184
	v_and_b32_e32 v207, 0xffff0000, v184
	v_max_f32_e32 v206, 0x2b800000, v206
	v_max_f32_e32 v207, 0x2b800000, v207
	v_rcp_f32_e32 v206, v206
	v_rcp_f32_e32 v207, v207
	v_lshlrev_b32_e32 v184, 16, v180
	v_and_b32_e32 v180, 0xffff0000, v180
	v_max_f32_e32 v184, 0x2b800000, v184
	v_max_f32_e32 v180, 0x2b800000, v180
	v_mul_f32_e32 v206, v206, v184
	v_mul_f32_e32 v207, v207, v180
	v_mul_f32_e32 v38, v38, v206
	v_mul_f32_e32 v39, v39, v207
	v_lshlrev_b32_e32 v208, 16, v185
	v_and_b32_e32 v209, 0xffff0000, v185
	v_max_f32_e32 v208, 0x2b800000, v208
	v_max_f32_e32 v209, 0x2b800000, v209
	v_rcp_f32_e32 v208, v208
	v_rcp_f32_e32 v209, v209
	v_lshlrev_b32_e32 v185, 16, v181
	v_and_b32_e32 v181, 0xffff0000, v181
	v_max_f32_e32 v185, 0x2b800000, v185
	v_max_f32_e32 v181, 0x2b800000, v181
	v_mul_f32_e32 v208, v208, v185
	v_mul_f32_e32 v209, v209, v181
	v_mul_f32_e32 v40, v40, v208
	v_mul_f32_e32 v41, v41, v209
	v_lshlrev_b32_e32 v210, 16, v186
	v_and_b32_e32 v211, 0xffff0000, v186
	v_max_f32_e32 v210, 0x2b800000, v210
	v_max_f32_e32 v211, 0x2b800000, v211
	v_rcp_f32_e32 v210, v210
	v_rcp_f32_e32 v211, v211
	v_lshlrev_b32_e32 v186, 16, v182
	v_and_b32_e32 v182, 0xffff0000, v182
	v_max_f32_e32 v186, 0x2b800000, v186
	v_max_f32_e32 v182, 0x2b800000, v182
	v_mul_f32_e32 v210, v210, v186
	v_mul_f32_e32 v211, v211, v182
	v_mul_f32_e32 v34, v34, v210
	v_mul_f32_e32 v35, v35, v211
	v_lshlrev_b32_e32 v206, 16, v187
	v_and_b32_e32 v207, 0xffff0000, v187
	v_max_f32_e32 v206, 0x2b800000, v206
	v_max_f32_e32 v207, 0x2b800000, v207
	v_rcp_f32_e32 v206, v206
	v_rcp_f32_e32 v207, v207
	v_lshlrev_b32_e32 v187, 16, v183
	v_and_b32_e32 v183, 0xffff0000, v183
	v_max_f32_e32 v187, 0x2b800000, v187
	v_max_f32_e32 v183, 0x2b800000, v183
	v_mul_f32_e32 v206, v206, v187
	v_mul_f32_e32 v207, v207, v183
	v_mul_f32_e32 v36, v36, v206
	v_mul_f32_e32 v37, v37, v207
	s_waitcnt vmcnt(6)
	v_lshlrev_b32_e32 v206, 16, v212
	v_and_b32_e32 v207, 0xffff0000, v212
	v_max_f32_e32 v206, 0x2b800000, v206
	v_max_f32_e32 v207, 0x2b800000, v207
	v_rcp_f32_e32 v206, v206
	v_rcp_f32_e32 v207, v207
	v_lshlrev_b32_e32 v212, 16, v188
	v_and_b32_e32 v188, 0xffff0000, v188
	v_max_f32_e32 v212, 0x2b800000, v212
	v_max_f32_e32 v188, 0x2b800000, v188
	v_mul_f32_e32 v206, v206, v212
	v_mul_f32_e32 v207, v207, v188
	v_mul_f32_e32 v30, v30, v206
	v_mul_f32_e32 v31, v31, v207
	v_lshlrev_b32_e32 v208, 16, v213
	v_and_b32_e32 v209, 0xffff0000, v213
	v_max_f32_e32 v208, 0x2b800000, v208
	v_max_f32_e32 v209, 0x2b800000, v209
	v_rcp_f32_e32 v208, v208
	v_rcp_f32_e32 v209, v209
	v_lshlrev_b32_e32 v213, 16, v189
	v_and_b32_e32 v189, 0xffff0000, v189
	v_max_f32_e32 v213, 0x2b800000, v213
	v_max_f32_e32 v189, 0x2b800000, v189
	v_mul_f32_e32 v208, v208, v213
	v_mul_f32_e32 v209, v209, v189
	v_mul_f32_e32 v32, v32, v208
	v_mul_f32_e32 v33, v33, v209
	v_lshlrev_b32_e32 v210, 16, v214
	v_and_b32_e32 v211, 0xffff0000, v214
	v_max_f32_e32 v210, 0x2b800000, v210
	v_max_f32_e32 v211, 0x2b800000, v211
	v_rcp_f32_e32 v210, v210
	v_rcp_f32_e32 v211, v211
	v_lshlrev_b32_e32 v214, 16, v190
	v_and_b32_e32 v190, 0xffff0000, v190
	v_max_f32_e32 v214, 0x2b800000, v214
	v_max_f32_e32 v190, 0x2b800000, v190
	v_mul_f32_e32 v210, v210, v214
	v_mul_f32_e32 v211, v211, v190
	v_mul_f32_e32 v26, v26, v210
	v_mul_f32_e32 v27, v27, v211
	v_lshlrev_b32_e32 v206, 16, v215
	v_and_b32_e32 v207, 0xffff0000, v215
	v_max_f32_e32 v206, 0x2b800000, v206
	v_max_f32_e32 v207, 0x2b800000, v207
	v_rcp_f32_e32 v206, v206
	v_rcp_f32_e32 v207, v207
	v_lshlrev_b32_e32 v215, 16, v191
	v_and_b32_e32 v191, 0xffff0000, v191
	v_max_f32_e32 v215, 0x2b800000, v215
	v_max_f32_e32 v191, 0x2b800000, v191
	v_mul_f32_e32 v206, v206, v215
	v_mul_f32_e32 v207, v207, v191
	v_mul_f32_e32 v28, v28, v206
	v_mul_f32_e32 v29, v29, v207
	s_waitcnt vmcnt(4)
	v_lshlrev_b32_e32 v206, 16, v220
	v_and_b32_e32 v207, 0xffff0000, v220
	v_max_f32_e32 v206, 0x2b800000, v206
	v_max_f32_e32 v207, 0x2b800000, v207
	v_rcp_f32_e32 v206, v206
	v_rcp_f32_e32 v207, v207
	v_lshlrev_b32_e32 v220, 16, v216
	v_and_b32_e32 v216, 0xffff0000, v216
	v_max_f32_e32 v220, 0x2b800000, v220
	v_max_f32_e32 v216, 0x2b800000, v216
	v_mul_f32_e32 v206, v206, v220
	v_mul_f32_e32 v207, v207, v216
	v_mul_f32_e32 v22, v22, v206
	v_mul_f32_e32 v23, v23, v207
	v_lshlrev_b32_e32 v208, 16, v221
	v_and_b32_e32 v209, 0xffff0000, v221
	v_max_f32_e32 v208, 0x2b800000, v208
	v_max_f32_e32 v209, 0x2b800000, v209
	v_rcp_f32_e32 v208, v208
	v_rcp_f32_e32 v209, v209
	v_lshlrev_b32_e32 v221, 16, v217
	v_and_b32_e32 v217, 0xffff0000, v217
	v_max_f32_e32 v221, 0x2b800000, v221
	v_max_f32_e32 v217, 0x2b800000, v217
	v_mul_f32_e32 v208, v208, v221
	v_mul_f32_e32 v209, v209, v217
	v_mul_f32_e32 v24, v24, v208
	v_mul_f32_e32 v25, v25, v209
	v_lshlrev_b32_e32 v210, 16, v222
	v_and_b32_e32 v211, 0xffff0000, v222
	v_max_f32_e32 v210, 0x2b800000, v210
	v_max_f32_e32 v211, 0x2b800000, v211
	v_rcp_f32_e32 v210, v210
	v_rcp_f32_e32 v211, v211
	v_lshlrev_b32_e32 v222, 16, v218
	v_and_b32_e32 v218, 0xffff0000, v218
	v_max_f32_e32 v222, 0x2b800000, v222
	v_max_f32_e32 v218, 0x2b800000, v218
	v_mul_f32_e32 v210, v210, v222
	v_mul_f32_e32 v211, v211, v218
	v_mul_f32_e32 v18, v18, v210
	v_mul_f32_e32 v19, v19, v211
	v_lshlrev_b32_e32 v206, 16, v223
	v_and_b32_e32 v207, 0xffff0000, v223
	v_max_f32_e32 v206, 0x2b800000, v206
	v_max_f32_e32 v207, 0x2b800000, v207
	v_rcp_f32_e32 v206, v206
	v_rcp_f32_e32 v207, v207
	v_lshlrev_b32_e32 v223, 16, v219
	v_and_b32_e32 v219, 0xffff0000, v219
	v_max_f32_e32 v223, 0x2b800000, v223
	v_max_f32_e32 v219, 0x2b800000, v219
	v_mul_f32_e32 v206, v206, v223
	v_mul_f32_e32 v207, v207, v219
	v_mul_f32_e32 v20, v20, v206
	v_mul_f32_e32 v21, v21, v207
	s_waitcnt vmcnt(2)
; __device__ __forceinline__ u32x4 pack8(f32x4 a, f32x4 b) { u32x4 w; w.x = cvt_pk_bf16(a[0], a[1]); w.y = cvt_pk_bf16(a[2], a[3]); w.z = cvt_pk_bf16(b[0], b[1]); w.w = cvt_pk_bf16(b[2], b[3]); return w; }
; __device__ __forceinline__ void unpack8(u32x4 w, f32x4& a, f32x4& b) { a = (f32x4){bf_lo(w.x), bf_hi(w.x), bf_lo(w.y), bf_hi(w.y)}; b = (f32x4){bf_lo(w.z), bf_hi(w.z), bf_lo(w.w), bf_hi(w.w)}; }
;     __device__ __forceinline__ void operator()(const f32x4 (&acc)[2][2][4][2], const Unit& u, int wr, int wc, int fr, int fq) const {
;     ...
;                     } else if (MODE == EP_MERGE0 || MODE == EP_MERGE1) {
;                         f32x4 g0, g1; unpack8(*(const u32x4*)(aux + row * ldaux + col), g0, g1);
;                         v0 = g0 * v0; v1 = g1 * v1;
;                         if (MODE == EP_MERGE1) { f32x4 o0, o1; unpack8(*(const u32x4*)((const bf16_t*)O + row * ldc + col), o0, o1); v0 = v0 + o0; v1 = v1 + o1; }
;                         *(u32x4*)((bf16_t*)O + row * ldc + col) = pack8(v0, v1);
; __global__ void __launch_bounds__(NTHR, 2) fwd(Args a) {
;     ...
;                 { pg8::Epi<pg8::EP_MERGE0> E{MRG, D, nullptr, PROJ + 3072, INW, nullptr}; run_gemm<pg8::EP_MERGE0>(lds, YCAT, D, (const bf16_t*)(wl + O_WA), M, D, 1024, E, wave); }
; #pragma unroll 1
;                 for (int j = 1; j < 3; ++j) { pg8::Epi<pg8::EP_MERGE1> E{MRG, D, nullptr, PROJ + 3072 + j * D, INW, nullptr};
;                     run_gemm<pg8::EP_MERGE1>(lds, YCAT + 512 + 512 * j, D, (const bf16_t*)(wl + (j == 1 ? O_WSG : O_WSSM)), M, D, 512, E, wave); }
	v_lshlrev_b32_e32 v206, 16, v228
	v_and_b32_e32 v207, 0xffff0000, v228
	v_max_f32_e32 v206, 0x2b800000, v206
	v_max_f32_e32 v207, 0x2b800000, v207
	v_rcp_f32_e32 v206, v206
	v_rcp_f32_e32 v207, v207
	v_lshlrev_b32_e32 v228, 16, v224
	v_and_b32_e32 v224, 0xffff0000, v224
	v_max_f32_e32 v228, 0x2b800000, v228
	v_max_f32_e32 v224, 0x2b800000, v224
	v_mul_f32_e32 v206, v206, v228
	v_mul_f32_e32 v207, v207, v224
	v_mul_f32_e32 v14, v14, v206
	v_mul_f32_e32 v15, v15, v207
	v_lshlrev_b32_e32 v208, 16, v229
	v_and_b32_e32 v209, 0xffff0000, v229
	v_max_f32_e32 v208, 0x2b800000, v208
	v_max_f32_e32 v209, 0x2b800000, v209
	v_rcp_f32_e32 v208, v208
	v_rcp_f32_e32 v209, v209
	v_lshlrev_b32_e32 v229, 16, v225
	v_and_b32_e32 v225, 0xffff0000, v225
	v_max_f32_e32 v229, 0x2b800000, v229
	v_max_f32_e32 v225, 0x2b800000, v225
	v_mul_f32_e32 v208, v208, v229
	v_mul_f32_e32 v209, v209, v225
	v_mul_f32_e32 v16, v16, v208
	v_mul_f32_e32 v17, v17, v209
	v_lshlrev_b32_e32 v210, 16, v230
	v_and_b32_e32 v211, 0xffff0000, v230
	v_max_f32_e32 v210, 0x2b800000, v210
	v_max_f32_e32 v211, 0x2b800000, v211
	v_rcp_f32_e32 v210, v210
	v_rcp_f32_e32 v211, v211
	v_lshlrev_b32_e32 v230, 16, v226
	v_and_b32_e32 v226, 0xffff0000, v226
	v_max_f32_e32 v230, 0x2b800000, v230
	v_max_f32_e32 v226, 0x2b800000, v226
	v_mul_f32_e32 v210, v210, v230
	v_mul_f32_e32 v211, v211, v226
	v_mul_f32_e32 v10, v10, v210
	v_mul_f32_e32 v11, v11, v211
	v_lshlrev_b32_e32 v206, 16, v231
	v_and_b32_e32 v207, 0xffff0000, v231
	v_max_f32_e32 v206, 0x2b800000, v206
	v_max_f32_e32 v207, 0x2b800000, v207
	v_rcp_f32_e32 v206, v206
	v_rcp_f32_e32 v207, v207
	v_lshlrev_b32_e32 v231, 16, v227
	v_and_b32_e32 v227, 0xffff0000, v227
	v_max_f32_e32 v231, 0x2b800000, v231
	v_max_f32_e32 v227, 0x2b800000, v227
	v_mul_f32_e32 v206, v206, v231
	v_mul_f32_e32 v207, v207, v227
	v_mul_f32_e32 v12, v12, v206
	v_mul_f32_e32 v13, v13, v207
	s_waitcnt vmcnt(0)
	v_lshlrev_b32_e32 v206, 16, v236
	v_and_b32_e32 v207, 0xffff0000, v236
	v_max_f32_e32 v206, 0x2b800000, v206
	v_max_f32_e32 v207, 0x2b800000, v207
	v_rcp_f32_e32 v206, v206
	v_rcp_f32_e32 v207, v207
	v_lshlrev_b32_e32 v236, 16, v232
	v_and_b32_e32 v232, 0xffff0000, v232
	v_max_f32_e32 v236, 0x2b800000, v236
	v_max_f32_e32 v232, 0x2b800000, v232
	v_mul_f32_e32 v206, v206, v236
	v_mul_f32_e32 v207, v207, v232
	v_mul_f32_e32 v6, v6, v206
	v_mul_f32_e32 v7, v7, v207
	v_lshlrev_b32_e32 v208, 16, v237
	v_and_b32_e32 v209, 0xffff0000, v237
	v_max_f32_e32 v208, 0x2b800000, v208
	v_max_f32_e32 v209, 0x2b800000, v209
	v_rcp_f32_e32 v208, v208
	v_rcp_f32_e32 v209, v209
	v_lshlrev_b32_e32 v237, 16, v233
	v_and_b32_e32 v233, 0xffff0000, v233
	v_max_f32_e32 v237, 0x2b800000, v237
	v_max_f32_e32 v233, 0x2b800000, v233
	v_mul_f32_e32 v208, v208, v237
	v_mul_f32_e32 v209, v209, v233
	v_mul_f32_e32 v8, v8, v208
	v_mul_f32_e32 v9, v9, v209
	v_lshlrev_b32_e32 v210, 16, v238
	v_and_b32_e32 v211, 0xffff0000, v238
	v_max_f32_e32 v210, 0x2b800000, v210
	v_max_f32_e32 v211, 0x2b800000, v211
	v_rcp_f32_e32 v210, v210
	v_rcp_f32_e32 v211, v211
	v_lshlrev_b32_e32 v238, 16, v234
	v_and_b32_e32 v234, 0xffff0000, v234
	v_max_f32_e32 v238, 0x2b800000, v238
	v_max_f32_e32 v234, 0x2b800000, v234
	v_mul_f32_e32 v210, v210, v238
	v_mul_f32_e32 v211, v211, v234
	v_mul_f32_e32 v2, v2, v210
	v_mul_f32_e32 v3, v3, v211
	v_lshlrev_b32_e32 v206, 16, v239
	v_and_b32_e32 v207, 0xffff0000, v239
	v_max_f32_e32 v206, 0x2b800000, v206
	v_max_f32_e32 v207, 0x2b800000, v207
	v_rcp_f32_e32 v206, v206
	v_rcp_f32_e32 v207, v207
	v_lshlrev_b32_e32 v239, 16, v235
	v_and_b32_e32 v235, 0xffff0000, v235
	v_max_f32_e32 v239, 0x2b800000, v239
	v_max_f32_e32 v235, 0x2b800000, v235
	v_mul_f32_e32 v206, v206, v239
	v_mul_f32_e32 v207, v207, v235
	v_mul_f32_e32 v4, v4, v206
	v_mul_f32_e32 v5, v5, v207
	s_branch .Lmg_nohook
.Lmg_epilogue:
	s_sub_u32 s98, s68, 0x4000000
	s_subb_u32 s99, s69, 0
	v_lshl_add_u32 v166, s42, 8, v148
	v_lshl_or_b32 v167, s41, 8, v152
	v_lshlrev_b32_e32 v167, 1, v167
	v_add_u32_e32 v167, 0x3800, v167
	v_add_u32_e32 v199, 0, v166
	v_mad_u32_u24 v205, v199, s81, v167
	global_load_dwordx4 v[140:143], v205, s[68:69]
	global_load_dwordx4 v[144:147], v205, s[68:69] offset:256
	v_add_u32_e32 v199, 16, v166
	v_mad_u32_u24 v205, v199, s81, v167
	global_load_dwordx4 v[154:157], v205, s[68:69]
	global_load_dwordx4 v[168:171], v205, s[68:69] offset:256
	v_add_u32_e32 v199, 32, v166
	v_mad_u32_u24 v205, v199, s81, v167
	global_load_dwordx4 v[172:175], v205, s[68:69]
	global_load_dwordx4 v[176:179], v205, s[68:69] offset:256
	v_add_u32_e32 v199, 48, v166
	v_mad_u32_u24 v205, v199, s81, v167
	global_load_dwordx4 v[180:183], v205, s[68:69]
	global_load_dwordx4 v[184:187], v205, s[68:69] offset:256
	v_add_u32_e32 v199, 128, v166
	v_mad_u32_u24 v205, v199, s81, v167
	global_load_dwordx4 v[188:191], v205, s[68:69]
	global_load_dwordx4 v[212:215], v205, s[68:69] offset:256
	v_add_u32_e32 v199, 144, v166
	v_mad_u32_u24 v205, v199, s81, v167
	global_load_dwordx4 v[216:219], v205, s[68:69]
	global_load_dwordx4 v[220:223], v205, s[68:69] offset:256
	v_add_u32_e32 v199, 160, v166
	v_mad_u32_u24 v205, v199, s81, v167
	global_load_dwordx4 v[224:227], v205, s[68:69]
	global_load_dwordx4 v[228:231], v205, s[68:69] offset:256
	v_add_u32_e32 v199, 176, v166
	v_mad_u32_u24 v205, v199, s81, v167
	global_load_dwordx4 v[232:235], v205, s[68:69]
	global_load_dwordx4 v[236:239], v205, s[68:69] offset:256
	v_add_u32_e32 v167, 0xffffc800, v167
	s_waitcnt vmcnt(15)
; __device__ __forceinline__ u32x4 pack8(f32x4 a, f32x4 b) { u32x4 w; w.x = cvt_pk_bf16(a[0], a[1]); w.y = cvt_pk_bf16(a[2], a[3]); w.z = cvt_pk_bf16(b[0], b[1]); w.w = cvt_pk_bf16(b[2], b[3]); return w; }
; __device__ __forceinline__ void unpack8(u32x4 w, f32x4& a, f32x4& b) { a = (f32x4){bf_lo(w.x), bf_hi(w.x), bf_lo(w.y), bf_hi(w.y)}; b = (f32x4){bf_lo(w.z), bf_hi(w.z), bf_lo(w.w), bf_hi(w.w)}; }
;     __device__ __forceinline__ void operator()(const f32x4 (&acc)[2][2][4][2], const Unit& u, int wr, int wc, int fr, int fq) const {
;     ...
;                     } else if (MODE == EP_MERGE0 || MODE == EP_MERGE1) {
;                         f32x4 g0, g1; unpack8(*(const u32x4*)(aux + row * ldaux + col), g0, g1);
;                         v0 = g0 * v0; v1 = g1 * v1;
;                         if (MODE == EP_MERGE1) { f32x4 o0, o1; unpack8(*(const u32x4*)((const bf16_t*)O + row * ldc + col), o0, o1); v0 = v0 + o0; v1 = v1 + o1; }
;                         *(u32x4*)((bf16_t*)O + row * ldc + col) = pack8(v0, v1);
	v_lshlrev_b32_e32 v206, 16, v140
	v_and_b32_e32 v207, 0xffff0000, v140
	v_max_f32_e32 v206, 0x2b800000, v206
	v_max_f32_e32 v207, 0x2b800000, v207
	v_mul_f32_e32 v126, v126, v206
	v_mul_f32_e32 v127, v127, v207
	v_cvt_pk_bf16_f32 v140, v126, v127
	v_lshlrev_b32_e32 v208, 16, v141
	v_and_b32_e32 v209, 0xffff0000, v141
	v_max_f32_e32 v208, 0x2b800000, v208
	v_max_f32_e32 v209, 0x2b800000, v209
	v_mul_f32_e32 v128, v128, v208
	v_mul_f32_e32 v129, v129, v209
	v_cvt_pk_bf16_f32 v141, v128, v129
	v_lshlrev_b32_e32 v210, 16, v142
	v_and_b32_e32 v211, 0xffff0000, v142
	v_max_f32_e32 v210, 0x2b800000, v210
	v_max_f32_e32 v211, 0x2b800000, v211
	v_mul_f32_e32 v122, v122, v210
	v_mul_f32_e32 v123, v123, v211
	v_cvt_pk_bf16_f32 v142, v122, v123
	v_lshlrev_b32_e32 v206, 16, v143
	v_and_b32_e32 v207, 0xffff0000, v143
	v_max_f32_e32 v206, 0x2b800000, v206
	v_max_f32_e32 v207, 0x2b800000, v207
	v_mul_f32_e32 v124, v124, v206
	v_mul_f32_e32 v125, v125, v207
	v_cvt_pk_bf16_f32 v143, v124, v125
	v_add_u32_e32 v199, 0, v166
	v_lshl_add_u32 v250, v199, 12, v167
	global_store_dwordx4 v250, v[140:143], s[98:99]
	s_waitcnt vmcnt(15)
	v_lshlrev_b32_e32 v206, 16, v144
	v_and_b32_e32 v207, 0xffff0000, v144
	v_max_f32_e32 v206, 0x2b800000, v206
	v_max_f32_e32 v207, 0x2b800000, v207
	v_mul_f32_e32 v118, v118, v206
	v_mul_f32_e32 v119, v119, v207
	v_cvt_pk_bf16_f32 v144, v118, v119
	v_lshlrev_b32_e32 v208, 16, v145
	v_and_b32_e32 v209, 0xffff0000, v145
	v_max_f32_e32 v208, 0x2b800000, v208
	v_max_f32_e32 v209, 0x2b800000, v209
	v_mul_f32_e32 v120, v120, v208
	v_mul_f32_e32 v121, v121, v209
	v_cvt_pk_bf16_f32 v145, v120, v121
	v_lshlrev_b32_e32 v210, 16, v146
	v_and_b32_e32 v211, 0xffff0000, v146
	v_max_f32_e32 v210, 0x2b800000, v210
	v_max_f32_e32 v211, 0x2b800000, v211
	v_mul_f32_e32 v114, v114, v210
	v_mul_f32_e32 v115, v115, v211
	v_cvt_pk_bf16_f32 v146, v114, v115
	v_lshlrev_b32_e32 v206, 16, v147
	v_and_b32_e32 v207, 0xffff0000, v147
	v_max_f32_e32 v206, 0x2b800000, v206
	v_max_f32_e32 v207, 0x2b800000, v207
	v_mul_f32_e32 v116, v116, v206
	v_mul_f32_e32 v117, v117, v207
	v_cvt_pk_bf16_f32 v147, v116, v117
	global_store_dwordx4 v250, v[144:147], s[98:99] offset:256
	s_waitcnt vmcnt(15)
	v_lshlrev_b32_e32 v206, 16, v154
	v_and_b32_e32 v207, 0xffff0000, v154
	v_max_f32_e32 v206, 0x2b800000, v206
	v_max_f32_e32 v207, 0x2b800000, v207
	v_mul_f32_e32 v110, v110, v206
	v_mul_f32_e32 v111, v111, v207
	v_cvt_pk_bf16_f32 v154, v110, v111
	v_lshlrev_b32_e32 v208, 16, v155
	v_and_b32_e32 v209, 0xffff0000, v155
	v_max_f32_e32 v208, 0x2b800000, v208
	v_max_f32_e32 v209, 0x2b800000, v209
	v_mul_f32_e32 v112, v112, v208
	v_mul_f32_e32 v113, v113, v209
	v_cvt_pk_bf16_f32 v155, v112, v113
	v_lshlrev_b32_e32 v210, 16, v156
	v_and_b32_e32 v211, 0xffff0000, v156
	v_max_f32_e32 v210, 0x2b800000, v210
	v_max_f32_e32 v211, 0x2b800000, v211
	v_mul_f32_e32 v106, v106, v210
	v_mul_f32_e32 v107, v107, v211
	v_cvt_pk_bf16_f32 v156, v106, v107
	v_lshlrev_b32_e32 v206, 16, v157
	v_and_b32_e32 v207, 0xffff0000, v157
	v_max_f32_e32 v206, 0x2b800000, v206
	v_max_f32_e32 v207, 0x2b800000, v207
	v_mul_f32_e32 v108, v108, v206
	v_mul_f32_e32 v109, v109, v207
	v_cvt_pk_bf16_f32 v157, v108, v109
	v_add_u32_e32 v199, 16, v166
	v_lshl_add_u32 v250, v199, 12, v167
	global_store_dwordx4 v250, v[154:157], s[98:99]
	s_waitcnt vmcnt(15)
	v_lshlrev_b32_e32 v206, 16, v168
	v_and_b32_e32 v207, 0xffff0000, v168
	v_max_f32_e32 v206, 0x2b800000, v206
	v_max_f32_e32 v207, 0x2b800000, v207
	v_mul_f32_e32 v102, v102, v206
	v_mul_f32_e32 v103, v103, v207
	v_cvt_pk_bf16_f32 v168, v102, v103
	v_lshlrev_b32_e32 v208, 16, v169
	v_and_b32_e32 v209, 0xffff0000, v169
	v_max_f32_e32 v208, 0x2b800000, v208
	v_max_f32_e32 v209, 0x2b800000, v209
	v_mul_f32_e32 v104, v104, v208
	v_mul_f32_e32 v105, v105, v209
	v_cvt_pk_bf16_f32 v169, v104, v105
	v_lshlrev_b32_e32 v210, 16, v170
	v_and_b32_e32 v211, 0xffff0000, v170
	v_max_f32_e32 v210, 0x2b800000, v210
	v_max_f32_e32 v211, 0x2b800000, v211
	v_mul_f32_e32 v98, v98, v210
	v_mul_f32_e32 v99, v99, v211
	v_cvt_pk_bf16_f32 v170, v98, v99
	v_lshlrev_b32_e32 v206, 16, v171
	v_and_b32_e32 v207, 0xffff0000, v171
	v_max_f32_e32 v206, 0x2b800000, v206
	v_max_f32_e32 v207, 0x2b800000, v207
	v_mul_f32_e32 v100, v100, v206
	v_mul_f32_e32 v101, v101, v207
	v_cvt_pk_bf16_f32 v171, v100, v101
	global_store_dwordx4 v250, v[168:171], s[98:99] offset:256
	s_waitcnt vmcnt(15)
	v_lshlrev_b32_e32 v206, 16, v172
	v_and_b32_e32 v207, 0xffff0000, v172
	v_max_f32_e32 v206, 0x2b800000, v206
	v_max_f32_e32 v207, 0x2b800000, v207
	v_mul_f32_e32 v94, v94, v206
	v_mul_f32_e32 v95, v95, v207
	v_cvt_pk_bf16_f32 v172, v94, v95
	v_lshlrev_b32_e32 v208, 16, v173
	v_and_b32_e32 v209, 0xffff0000, v173
	v_max_f32_e32 v208, 0x2b800000, v208
	v_max_f32_e32 v209, 0x2b800000, v209
	v_mul_f32_e32 v96, v96, v208
	v_mul_f32_e32 v97, v97, v209
	v_cvt_pk_bf16_f32 v173, v96, v97
	v_lshlrev_b32_e32 v210, 16, v174
	v_and_b32_e32 v211, 0xffff0000, v174
	v_max_f32_e32 v210, 0x2b800000, v210
	v_max_f32_e32 v211, 0x2b800000, v211
	v_mul_f32_e32 v90, v90, v210
	v_mul_f32_e32 v91, v91, v211
	v_cvt_pk_bf16_f32 v174, v90, v91
	v_lshlrev_b32_e32 v206, 16, v175
	v_and_b32_e32 v207, 0xffff0000, v175
	v_max_f32_e32 v206, 0x2b800000, v206
	v_max_f32_e32 v207, 0x2b800000, v207
	v_mul_f32_e32 v92, v92, v206
	v_mul_f32_e32 v93, v93, v207
	v_cvt_pk_bf16_f32 v175, v92, v93
	v_add_u32_e32 v199, 32, v166
	v_lshl_add_u32 v250, v199, 12, v167
	global_store_dwordx4 v250, v[172:175], s[98:99]
	s_waitcnt vmcnt(15)
; __device__ __forceinline__ u32x4 pack8(f32x4 a, f32x4 b) { u32x4 w; w.x = cvt_pk_bf16(a[0], a[1]); w.y = cvt_pk_bf16(a[2], a[3]); w.z = cvt_pk_bf16(b[0], b[1]); w.w = cvt_pk_bf16(b[2], b[3]); return w; }
; __device__ __forceinline__ void unpack8(u32x4 w, f32x4& a, f32x4& b) { a = (f32x4){bf_lo(w.x), bf_hi(w.x), bf_lo(w.y), bf_hi(w.y)}; b = (f32x4){bf_lo(w.z), bf_hi(w.z), bf_lo(w.w), bf_hi(w.w)}; }
;     __device__ __forceinline__ void operator()(const f32x4 (&acc)[2][2][4][2], const Unit& u, int wr, int wc, int fr, int fq) const {
;     ...
;                     } else if (MODE == EP_MERGE0 || MODE == EP_MERGE1) {
;                         f32x4 g0, g1; unpack8(*(const u32x4*)(aux + row * ldaux + col), g0, g1);
;                         v0 = g0 * v0; v1 = g1 * v1;
;                         if (MODE == EP_MERGE1) { f32x4 o0, o1; unpack8(*(const u32x4*)((const bf16_t*)O + row * ldc + col), o0, o1); v0 = v0 + o0; v1 = v1 + o1; }
;                         *(u32x4*)((bf16_t*)O + row * ldc + col) = pack8(v0, v1);
	v_lshlrev_b32_e32 v206, 16, v176
	v_and_b32_e32 v207, 0xffff0000, v176
	v_max_f32_e32 v206, 0x2b800000, v206
	v_max_f32_e32 v207, 0x2b800000, v207
	v_mul_f32_e32 v86, v86, v206
	v_mul_f32_e32 v87, v87, v207
	v_cvt_pk_bf16_f32 v176, v86, v87
	v_lshlrev_b32_e32 v208, 16, v177
	v_and_b32_e32 v209, 0xffff0000, v177
	v_max_f32_e32 v208, 0x2b800000, v208
	v_max_f32_e32 v209, 0x2b800000, v209
	v_mul_f32_e32 v88, v88, v208
	v_mul_f32_e32 v89, v89, v209
	v_cvt_pk_bf16_f32 v177, v88, v89
	v_lshlrev_b32_e32 v210, 16, v178
	v_and_b32_e32 v211, 0xffff0000, v178
	v_max_f32_e32 v210, 0x2b800000, v210
	v_max_f32_e32 v211, 0x2b800000, v211
	v_mul_f32_e32 v82, v82, v210
	v_mul_f32_e32 v83, v83, v211
	v_cvt_pk_bf16_f32 v178, v82, v83
	v_lshlrev_b32_e32 v206, 16, v179
	v_and_b32_e32 v207, 0xffff0000, v179
	v_max_f32_e32 v206, 0x2b800000, v206
	v_max_f32_e32 v207, 0x2b800000, v207
	v_mul_f32_e32 v84, v84, v206
	v_mul_f32_e32 v85, v85, v207
	v_cvt_pk_bf16_f32 v179, v84, v85
	global_store_dwordx4 v250, v[176:179], s[98:99] offset:256
	s_waitcnt vmcnt(15)
	v_lshlrev_b32_e32 v206, 16, v180
	v_and_b32_e32 v207, 0xffff0000, v180
	v_max_f32_e32 v206, 0x2b800000, v206
	v_max_f32_e32 v207, 0x2b800000, v207
	v_mul_f32_e32 v78, v78, v206
	v_mul_f32_e32 v79, v79, v207
	v_cvt_pk_bf16_f32 v180, v78, v79
	v_lshlrev_b32_e32 v208, 16, v181
	v_and_b32_e32 v209, 0xffff0000, v181
	v_max_f32_e32 v208, 0x2b800000, v208
	v_max_f32_e32 v209, 0x2b800000, v209
	v_mul_f32_e32 v80, v80, v208
	v_mul_f32_e32 v81, v81, v209
	v_cvt_pk_bf16_f32 v181, v80, v81
	v_lshlrev_b32_e32 v210, 16, v182
	v_and_b32_e32 v211, 0xffff0000, v182
	v_max_f32_e32 v210, 0x2b800000, v210
	v_max_f32_e32 v211, 0x2b800000, v211
	v_mul_f32_e32 v74, v74, v210
	v_mul_f32_e32 v75, v75, v211
	v_cvt_pk_bf16_f32 v182, v74, v75
	v_lshlrev_b32_e32 v206, 16, v183
	v_and_b32_e32 v207, 0xffff0000, v183
	v_max_f32_e32 v206, 0x2b800000, v206
	v_max_f32_e32 v207, 0x2b800000, v207
	v_mul_f32_e32 v76, v76, v206
	v_mul_f32_e32 v77, v77, v207
	v_cvt_pk_bf16_f32 v183, v76, v77
	v_add_u32_e32 v199, 48, v166
	v_lshl_add_u32 v250, v199, 12, v167
	global_store_dwordx4 v250, v[180:183], s[98:99]
	s_waitcnt vmcnt(15)
	v_lshlrev_b32_e32 v206, 16, v184
	v_and_b32_e32 v207, 0xffff0000, v184
	v_max_f32_e32 v206, 0x2b800000, v206
	v_max_f32_e32 v207, 0x2b800000, v207
	v_mul_f32_e32 v70, v70, v206
	v_mul_f32_e32 v71, v71, v207
	v_cvt_pk_bf16_f32 v184, v70, v71
	v_lshlrev_b32_e32 v208, 16, v185
	v_and_b32_e32 v209, 0xffff0000, v185
	v_max_f32_e32 v208, 0x2b800000, v208
	v_max_f32_e32 v209, 0x2b800000, v209
	v_mul_f32_e32 v72, v72, v208
	v_mul_f32_e32 v73, v73, v209
	v_cvt_pk_bf16_f32 v185, v72, v73
	v_lshlrev_b32_e32 v210, 16, v186
	v_and_b32_e32 v211, 0xffff0000, v186
	v_max_f32_e32 v210, 0x2b800000, v210
	v_max_f32_e32 v211, 0x2b800000, v211
	v_mul_f32_e32 v66, v66, v210
	v_mul_f32_e32 v67, v67, v211
	v_cvt_pk_bf16_f32 v186, v66, v67
	v_lshlrev_b32_e32 v206, 16, v187
	v_and_b32_e32 v207, 0xffff0000, v187
	v_max_f32_e32 v206, 0x2b800000, v206
	v_max_f32_e32 v207, 0x2b800000, v207
	v_mul_f32_e32 v68, v68, v206
	v_mul_f32_e32 v69, v69, v207
	v_cvt_pk_bf16_f32 v187, v68, v69
	global_store_dwordx4 v250, v[184:187], s[98:99] offset:256
	s_waitcnt vmcnt(15)
	v_lshlrev_b32_e32 v206, 16, v188
	v_and_b32_e32 v207, 0xffff0000, v188
	v_max_f32_e32 v206, 0x2b800000, v206
	v_max_f32_e32 v207, 0x2b800000, v207
	v_mul_f32_e32 v62, v62, v206
	v_mul_f32_e32 v63, v63, v207
	v_cvt_pk_bf16_f32 v188, v62, v63
	v_lshlrev_b32_e32 v208, 16, v189
	v_and_b32_e32 v209, 0xffff0000, v189
	v_max_f32_e32 v208, 0x2b800000, v208
	v_max_f32_e32 v209, 0x2b800000, v209
	v_mul_f32_e32 v64, v64, v208
	v_mul_f32_e32 v65, v65, v209
	v_cvt_pk_bf16_f32 v189, v64, v65
	v_lshlrev_b32_e32 v210, 16, v190
	v_and_b32_e32 v211, 0xffff0000, v190
	v_max_f32_e32 v210, 0x2b800000, v210
	v_max_f32_e32 v211, 0x2b800000, v211
	v_mul_f32_e32 v58, v58, v210
	v_mul_f32_e32 v59, v59, v211
	v_cvt_pk_bf16_f32 v190, v58, v59
	v_lshlrev_b32_e32 v206, 16, v191
	v_and_b32_e32 v207, 0xffff0000, v191
	v_max_f32_e32 v206, 0x2b800000, v206
	v_max_f32_e32 v207, 0x2b800000, v207
	v_mul_f32_e32 v60, v60, v206
	v_mul_f32_e32 v61, v61, v207
	v_cvt_pk_bf16_f32 v191, v60, v61
	v_add_u32_e32 v199, 128, v166
	v_lshl_add_u32 v250, v199, 12, v167
	global_store_dwordx4 v250, v[188:191], s[98:99]
	s_waitcnt vmcnt(15)
	v_lshlrev_b32_e32 v206, 16, v212
	v_and_b32_e32 v207, 0xffff0000, v212
	v_max_f32_e32 v206, 0x2b800000, v206
	v_max_f32_e32 v207, 0x2b800000, v207
	v_mul_f32_e32 v54, v54, v206
	v_mul_f32_e32 v55, v55, v207
	v_cvt_pk_bf16_f32 v212, v54, v55
	v_lshlrev_b32_e32 v208, 16, v213
	v_and_b32_e32 v209, 0xffff0000, v213
	v_max_f32_e32 v208, 0x2b800000, v208
	v_max_f32_e32 v209, 0x2b800000, v209
	v_mul_f32_e32 v56, v56, v208
	v_mul_f32_e32 v57, v57, v209
	v_cvt_pk_bf16_f32 v213, v56, v57
	v_lshlrev_b32_e32 v210, 16, v214
	v_and_b32_e32 v211, 0xffff0000, v214
	v_max_f32_e32 v210, 0x2b800000, v210
	v_max_f32_e32 v211, 0x2b800000, v211
	v_mul_f32_e32 v50, v50, v210
	v_mul_f32_e32 v51, v51, v211
	v_cvt_pk_bf16_f32 v214, v50, v51
	v_lshlrev_b32_e32 v206, 16, v215
	v_and_b32_e32 v207, 0xffff0000, v215
	v_max_f32_e32 v206, 0x2b800000, v206
	v_max_f32_e32 v207, 0x2b800000, v207
	v_mul_f32_e32 v52, v52, v206
	v_mul_f32_e32 v53, v53, v207
	v_cvt_pk_bf16_f32 v215, v52, v53
	global_store_dwordx4 v250, v[212:215], s[98:99] offset:256
	s_waitcnt vmcnt(15)
; __device__ __forceinline__ u32x4 pack8(f32x4 a, f32x4 b) { u32x4 w; w.x = cvt_pk_bf16(a[0], a[1]); w.y = cvt_pk_bf16(a[2], a[3]); w.z = cvt_pk_bf16(b[0], b[1]); w.w = cvt_pk_bf16(b[2], b[3]); return w; }
; __device__ __forceinline__ void unpack8(u32x4 w, f32x4& a, f32x4& b) { a = (f32x4){bf_lo(w.x), bf_hi(w.x), bf_lo(w.y), bf_hi(w.y)}; b = (f32x4){bf_lo(w.z), bf_hi(w.z), bf_lo(w.w), bf_hi(w.w)}; }
;     __device__ __forceinline__ void operator()(const f32x4 (&acc)[2][2][4][2], const Unit& u, int wr, int wc, int fr, int fq) const {
;     ...
;                     } else if (MODE == EP_MERGE0 || MODE == EP_MERGE1) {
;                         f32x4 g0, g1; unpack8(*(const u32x4*)(aux + row * ldaux + col), g0, g1);
;                         v0 = g0 * v0; v1 = g1 * v1;
;                         if (MODE == EP_MERGE1) { f32x4 o0, o1; unpack8(*(const u32x4*)((const bf16_t*)O + row * ldc + col), o0, o1); v0 = v0 + o0; v1 = v1 + o1; }
;                         *(u32x4*)((bf16_t*)O + row * ldc + col) = pack8(v0, v1);
	v_lshlrev_b32_e32 v206, 16, v216
	v_and_b32_e32 v207, 0xffff0000, v216
	v_max_f32_e32 v206, 0x2b800000, v206
	v_max_f32_e32 v207, 0x2b800000, v207
	v_mul_f32_e32 v46, v46, v206
	v_mul_f32_e32 v47, v47, v207
	v_cvt_pk_bf16_f32 v216, v46, v47
	v_lshlrev_b32_e32 v208, 16, v217
	v_and_b32_e32 v209, 0xffff0000, v217
	v_max_f32_e32 v208, 0x2b800000, v208
	v_max_f32_e32 v209, 0x2b800000, v209
	v_mul_f32_e32 v48, v48, v208
	v_mul_f32_e32 v49, v49, v209
	v_cvt_pk_bf16_f32 v217, v48, v49
	v_lshlrev_b32_e32 v210, 16, v218
	v_and_b32_e32 v211, 0xffff0000, v218
	v_max_f32_e32 v210, 0x2b800000, v210
	v_max_f32_e32 v211, 0x2b800000, v211
	v_mul_f32_e32 v42, v42, v210
	v_mul_f32_e32 v43, v43, v211
	v_cvt_pk_bf16_f32 v218, v42, v43
	v_lshlrev_b32_e32 v206, 16, v219
	v_and_b32_e32 v207, 0xffff0000, v219
	v_max_f32_e32 v206, 0x2b800000, v206
	v_max_f32_e32 v207, 0x2b800000, v207
	v_mul_f32_e32 v44, v44, v206
	v_mul_f32_e32 v45, v45, v207
	v_cvt_pk_bf16_f32 v219, v44, v45
	v_add_u32_e32 v199, 144, v166
	v_lshl_add_u32 v250, v199, 12, v167
	global_store_dwordx4 v250, v[216:219], s[98:99]
	s_waitcnt vmcnt(15)
	v_lshlrev_b32_e32 v206, 16, v220
	v_and_b32_e32 v207, 0xffff0000, v220
	v_max_f32_e32 v206, 0x2b800000, v206
	v_max_f32_e32 v207, 0x2b800000, v207
	v_mul_f32_e32 v38, v38, v206
	v_mul_f32_e32 v39, v39, v207
	v_cvt_pk_bf16_f32 v220, v38, v39
	v_lshlrev_b32_e32 v208, 16, v221
	v_and_b32_e32 v209, 0xffff0000, v221
	v_max_f32_e32 v208, 0x2b800000, v208
	v_max_f32_e32 v209, 0x2b800000, v209
	v_mul_f32_e32 v40, v40, v208
	v_mul_f32_e32 v41, v41, v209
	v_cvt_pk_bf16_f32 v221, v40, v41
	v_lshlrev_b32_e32 v210, 16, v222
	v_and_b32_e32 v211, 0xffff0000, v222
	v_max_f32_e32 v210, 0x2b800000, v210
	v_max_f32_e32 v211, 0x2b800000, v211
	v_mul_f32_e32 v34, v34, v210
	v_mul_f32_e32 v35, v35, v211
	v_cvt_pk_bf16_f32 v222, v34, v35
	v_lshlrev_b32_e32 v206, 16, v223
	v_and_b32_e32 v207, 0xffff0000, v223
	v_max_f32_e32 v206, 0x2b800000, v206
	v_max_f32_e32 v207, 0x2b800000, v207
	v_mul_f32_e32 v36, v36, v206
	v_mul_f32_e32 v37, v37, v207
	v_cvt_pk_bf16_f32 v223, v36, v37
	global_store_dwordx4 v250, v[220:223], s[98:99] offset:256
	s_waitcnt vmcnt(15)
	v_lshlrev_b32_e32 v206, 16, v224
	v_and_b32_e32 v207, 0xffff0000, v224
	v_max_f32_e32 v206, 0x2b800000, v206
	v_max_f32_e32 v207, 0x2b800000, v207
	v_mul_f32_e32 v30, v30, v206
	v_mul_f32_e32 v31, v31, v207
	v_cvt_pk_bf16_f32 v224, v30, v31
	v_lshlrev_b32_e32 v208, 16, v225
	v_and_b32_e32 v209, 0xffff0000, v225
	v_max_f32_e32 v208, 0x2b800000, v208
	v_max_f32_e32 v209, 0x2b800000, v209
	v_mul_f32_e32 v32, v32, v208
	v_mul_f32_e32 v33, v33, v209
	v_cvt_pk_bf16_f32 v225, v32, v33
	v_lshlrev_b32_e32 v210, 16, v226
	v_and_b32_e32 v211, 0xffff0000, v226
	v_max_f32_e32 v210, 0x2b800000, v210
	v_max_f32_e32 v211, 0x2b800000, v211
	v_mul_f32_e32 v26, v26, v210
	v_mul_f32_e32 v27, v27, v211
	v_cvt_pk_bf16_f32 v226, v26, v27
	v_lshlrev_b32_e32 v206, 16, v227
	v_and_b32_e32 v207, 0xffff0000, v227
	v_max_f32_e32 v206, 0x2b800000, v206
	v_max_f32_e32 v207, 0x2b800000, v207
	v_mul_f32_e32 v28, v28, v206
	v_mul_f32_e32 v29, v29, v207
	v_cvt_pk_bf16_f32 v227, v28, v29
	v_add_u32_e32 v199, 160, v166
	v_lshl_add_u32 v250, v199, 12, v167
	global_store_dwordx4 v250, v[224:227], s[98:99]
	s_waitcnt vmcnt(15)
	v_lshlrev_b32_e32 v206, 16, v228
	v_and_b32_e32 v207, 0xffff0000, v228
	v_max_f32_e32 v206, 0x2b800000, v206
	v_max_f32_e32 v207, 0x2b800000, v207
	v_mul_f32_e32 v22, v22, v206
	v_mul_f32_e32 v23, v23, v207
	v_cvt_pk_bf16_f32 v228, v22, v23
	v_lshlrev_b32_e32 v208, 16, v229
	v_and_b32_e32 v209, 0xffff0000, v229
	v_max_f32_e32 v208, 0x2b800000, v208
	v_max_f32_e32 v209, 0x2b800000, v209
	v_mul_f32_e32 v24, v24, v208
	v_mul_f32_e32 v25, v25, v209
	v_cvt_pk_bf16_f32 v229, v24, v25
	v_lshlrev_b32_e32 v210, 16, v230
	v_and_b32_e32 v211, 0xffff0000, v230
	v_max_f32_e32 v210, 0x2b800000, v210
	v_max_f32_e32 v211, 0x2b800000, v211
	v_mul_f32_e32 v18, v18, v210
	v_mul_f32_e32 v19, v19, v211
	v_cvt_pk_bf16_f32 v230, v18, v19
	v_lshlrev_b32_e32 v206, 16, v231
	v_and_b32_e32 v207, 0xffff0000, v231
	v_max_f32_e32 v206, 0x2b800000, v206
	v_max_f32_e32 v207, 0x2b800000, v207
	v_mul_f32_e32 v20, v20, v206
	v_mul_f32_e32 v21, v21, v207
	v_cvt_pk_bf16_f32 v231, v20, v21
	global_store_dwordx4 v250, v[228:231], s[98:99] offset:256
	s_waitcnt vmcnt(15)
	v_lshlrev_b32_e32 v206, 16, v232
	v_and_b32_e32 v207, 0xffff0000, v232
	v_max_f32_e32 v206, 0x2b800000, v206
	v_max_f32_e32 v207, 0x2b800000, v207
	v_mul_f32_e32 v14, v14, v206
	v_mul_f32_e32 v15, v15, v207
	v_cvt_pk_bf16_f32 v232, v14, v15
	v_lshlrev_b32_e32 v208, 16, v233
	v_and_b32_e32 v209, 0xffff0000, v233
	v_max_f32_e32 v208, 0x2b800000, v208
	v_max_f32_e32 v209, 0x2b800000, v209
	v_mul_f32_e32 v16, v16, v208
	v_mul_f32_e32 v17, v17, v209
	v_cvt_pk_bf16_f32 v233, v16, v17
	v_lshlrev_b32_e32 v210, 16, v234
	v_and_b32_e32 v211, 0xffff0000, v234
	v_max_f32_e32 v210, 0x2b800000, v210
	v_max_f32_e32 v211, 0x2b800000, v211
	v_mul_f32_e32 v10, v10, v210
	v_mul_f32_e32 v11, v11, v211
	v_cvt_pk_bf16_f32 v234, v10, v11
	v_lshlrev_b32_e32 v206, 16, v235
	v_and_b32_e32 v207, 0xffff0000, v235
	v_max_f32_e32 v206, 0x2b800000, v206
	v_max_f32_e32 v207, 0x2b800000, v207
	v_mul_f32_e32 v12, v12, v206
	v_mul_f32_e32 v13, v13, v207
	v_cvt_pk_bf16_f32 v235, v12, v13
	v_add_u32_e32 v199, 176, v166
	v_lshl_add_u32 v250, v199, 12, v167
	global_store_dwordx4 v250, v[232:235], s[98:99]
	s_waitcnt vmcnt(15)
	v_lshlrev_b32_e32 v206, 16, v236
	v_and_b32_e32 v207, 0xffff0000, v236
	v_max_f32_e32 v206, 0x2b800000, v206
	v_max_f32_e32 v207, 0x2b800000, v207
	v_mul_f32_e32 v6, v6, v206
	v_mul_f32_e32 v7, v7, v207
	v_cvt_pk_bf16_f32 v236, v6, v7
	v_lshlrev_b32_e32 v208, 16, v237
	v_and_b32_e32 v209, 0xffff0000, v237
	v_max_f32_e32 v208, 0x2b800000, v208
	v_max_f32_e32 v209, 0x2b800000, v209
	v_mul_f32_e32 v8, v8, v208
	v_mul_f32_e32 v9, v9, v209
	v_cvt_pk_bf16_f32 v237, v8, v9
	v_lshlrev_b32_e32 v210, 16, v238
	v_and_b32_e32 v211, 0xffff0000, v238
	v_max_f32_e32 v210, 0x2b800000, v210
	v_max_f32_e32 v211, 0x2b800000, v211
	v_mul_f32_e32 v2, v2, v210
	v_mul_f32_e32 v3, v3, v211
	v_cvt_pk_bf16_f32 v238, v2, v3
	v_lshlrev_b32_e32 v206, 16, v239
	v_and_b32_e32 v207, 0xffff0000, v239
	v_max_f32_e32 v206, 0x2b800000, v206
	v_max_f32_e32 v207, 0x2b800000, v207
	v_mul_f32_e32 v4, v4, v206
	v_mul_f32_e32 v5, v5, v207
	v_cvt_pk_bf16_f32 v239, v4, v5
	global_store_dwordx4 v250, v[236:239], s[98:99] offset:256
	s_branch .LBB0_487

; __device__ __forceinline__ void convert_phase(CArgs* ap, int l, LAS unsigned char* lds, int gw, int NGW, int wave, int lane) {
;     ...
;                 case 0: W = ap->in[2] + (size_t)l * D * INW; K = D; N = INW; off = O_WIN; break;
;                 case 1: W = ap->in[21] + (size_t)l * 1024 * D; K = 1024; N = D; off = O_WA; break;
;                 case 2: W = ap->in[22] + (size_t)l * 512 * D; K = 512; N = D; off = O_WSG; break;
;                 case 3: W = ap->in[23] + (size_t)l * 512 * D; K = 512; N = D; off = O_WSSM; break;
;                 case 4: W = ap->in[24] + (size_t)l * D * D; K = D; N = D; off = O_WOUT; break;
;                 case 5: W = ap->in[26] + (size_t)l * D * NUP; K = D; N = NUP; off = O_WUP; break;
;                 case 6: W = ap->in[29] + (size_t)l * DFF * D; K = DFF; N = D; off = O_WDN; break;
;                 default: W = ap->in[19] + (size_t)l * 512 * 512; K = 512; N = 512; off = O_WGLU; break;
.LBB0_522:
	s_andn2_b64 vcc, exec, s[2:3]
	v_readlane_b32 s2, v254, 10
	v_readlane_b32 s4, v253, 60
	s_movk_i32 s19, 0x800
	s_mov_b64 s[12:13], 0x2c00000
	s_movk_i32 s18, 0x800
	v_readlane_b32 s3, v254, 11
	v_readlane_b32 s5, v253, 61
	s_cbranch_vccnz .LBB0_524
	v_readlane_b32 s2, v253, 62
	v_readlane_b32 s4, v254, 33
	s_movk_i32 s18, 0x200
	s_mov_b64 s[12:13], 0x2400c00
	v_readlane_b32 s3, v253, 63
	v_readlane_b32 s5, v254, 34

; __device__ __forceinline__ void titem_load(const float* W, int N, int item, int lane, float (&wv)[32]) {
;     const int nblk = N / 32, kb = item / nblk, nb = item % nblk;
;     const float* wp = W + (size_t)(64 * kb + (lane >> 5)) * N + 32 * nb + (lane & 31);
; #pragma unroll
;     for (int i = 0; i < 32; ++i) wv[i] = __builtin_nontemporal_load(wp + (size_t)(2 * i) * N);
; }
; __device__ __forceinline__ void convert_phase(CArgs* ap, int l, LAS unsigned char* lds, int gw, int NGW, int wave, int lane) {
;     ...
;             const int nitems = (K / 64) * (N / 32);
;             const float* gain = mi == 0 ? ap->in[1] + l * D : (mi == 5 ? ap->in[25] + l * D : nullptr);
;             float wc[32], wn[32];
;             int it = gw;
;             if (it < nitems) titem_load(W, N, it, lane, wc);
.LBB0_540:
	s_mov_b32 s101, s18
	s_add_i32 s99, s78, -1
	s_cmp_lt_u32 s99, 3
	s_cselect_b32 s101, 0x800, s101
	s_waitcnt lgkmcnt(0)
	s_add_u32 s34, s0, s2
	s_addc_u32 s35, s1, s3
	s_lshr_b32 s10, s19, 5
	v_cvt_f32_u32_e32 v0, s10
	s_lshr_b32 s0, s18, 6
	s_mul_i32 s11, s10, s0
	s_cmp_lt_i32 s97, s11
	v_rcp_iflag_f32_e32 v72, v0
	s_cselect_b64 s[0:1], -1, 0
	s_cmp_ge_i32 s97, s11
	s_mul_i32 s36, s19, 6
	s_mul_i32 s38, s19, 10
	s_mul_i32 s40, s19, 12
	s_mul_i32 s42, s19, 14
	s_mul_i32 s44, s19, 18
	s_mul_i32 s46, s19, 20
	s_mul_i32 s48, s19, 22
	s_mul_i32 s50, s19, 24
	s_mul_i32 s52, s19, 26
	s_mul_i32 s54, s19, 28
	s_mul_i32 s56, s19, 30
	s_mul_i32 s58, s19, 34
	s_mul_i32 s60, s19, 36
	s_mul_i32 s62, s19, 38
	s_mul_i32 s64, s19, 40
	s_mul_i32 s66, s19, 42
	s_mul_i32 s68, s19, 44
	s_mul_i32 s70, s19, 46
	s_mul_i32 s72, s19, 48
	s_mul_i32 s74, s19, 50
	s_mul_i32 s76, s19, 52
	s_mul_i32 s82, s19, 54
	s_mul_i32 s86, s19, 56
	s_mul_i32 s88, s19, 58
	s_mul_i32 s90, s19, 60
	s_mul_i32 s92, s19, 62
	v_lshlrev_b32_e32 v0, 2, v66
	s_cbranch_scc1 .LBB0_542
	s_waitcnt vmcnt(31)
	v_mul_f32_e32 v34, 0x4f7ffffe, v72
	v_cvt_u32_f32_e32 v34, v34
	s_sub_i32 s2, 0, s10
	v_readlane_b32 s5, v253, 0
	s_mov_b32 s37, s79
	v_readfirstlane_b32 s3, v34
	s_mul_i32 s2, s2, s3
	s_mul_hi_u32 s2, s3, s2
	s_add_i32 s3, s3, s2
	s_mul_hi_u32 s2, s5, s3
	s_mul_i32 s3, s2, s10
	s_sub_i32 s3, s5, s3
	s_add_i32 s4, s2, 1
	s_sub_i32 s5, s3, s10
	s_cmp_ge_u32 s3, s10
	s_cselect_b32 s2, s4, s2
	s_cselect_b32 s3, s5, s3
	s_add_i32 s4, s2, 1
	s_cmp_ge_u32 s3, s10
	s_cselect_b32 s2, s4, s2
	v_readlane_b32 s3, v252, 63
	s_xor_b32 s2, s2, s3
	s_sub_i32 s2, s2, s3
	s_mul_i32 s3, s2, s10
	s_lshl_b32 s2, s2, 6
	v_or_b32_e32 v34, s2, v67
	s_ashr_i32 s2, s2, 31
	s_sub_i32 s4, s97, s3
	s_mul_i32 s5, s2, s19
	s_waitcnt vmcnt(30)
	v_mad_u64_u32 v[34:35], s[2:3], v34, s19, 0
	v_add_u32_e32 v35, s5, v35
	s_lshl_b32 s2, s4, 5
	v_lshl_add_u64 v[34:35], v[34:35], 2, s[34:35]
	s_ashr_i32 s3, s2, 31
	v_lshl_add_u64 v[34:35], s[2:3], 2, v[34:35]
	s_waitcnt vmcnt(6)
	v_lshl_add_u64 v[58:59], v[34:35], 0, v[0:1]
	s_lshl_b32 s2, s19, 1
	s_mov_b32 s3, s79
	v_lshl_add_u64 v[36:37], s[2:3], 2, v[58:59]
	s_lshl_b32 s2, s19, 2
	v_lshl_add_u64 v[38:39], s[2:3], 2, v[58:59]
	s_lshl_b32 s2, s19, 3
	s_mov_b32 s39, s79
	s_mov_b32 s41, s79
	s_mov_b32 s43, s79
	v_lshl_add_u64 v[40:41], s[36:37], 2, v[58:59]
	v_lshl_add_u64 v[42:43], s[2:3], 2, v[58:59]
	v_lshl_add_u64 v[44:45], s[38:39], 2, v[58:59]
	v_lshl_add_u64 v[46:47], s[40:41], 2, v[58:59]
	v_lshl_add_u64 v[48:49], s[42:43], 2, v[58:59]
	s_lshl_b32 s2, s19, 4
	s_mov_b32 s45, s79
	s_mov_b32 s47, s79
	s_mov_b32 s49, s79
	s_mov_b32 s51, s79
	s_mov_b32 s53, s79
	s_mov_b32 s55, s79
	s_mov_b32 s57, s79
	global_load_dword v34, v[58:59], off nt
	global_load_dword v35, v[36:37], off nt
	s_nop 0
	global_load_dword v36, v[38:39], off nt
	global_load_dword v37, v[40:41], off nt
	s_nop 0
	global_load_dword v38, v[42:43], off nt
	global_load_dword v39, v[44:45], off nt
	global_load_dword v40, v[46:47], off nt
	global_load_dword v41, v[48:49], off nt
	v_lshl_add_u64 v[42:43], s[2:3], 2, v[58:59]
	v_lshl_add_u64 v[44:45], s[44:45], 2, v[58:59]
	v_lshl_add_u64 v[46:47], s[46:47], 2, v[58:59]
	v_lshl_add_u64 v[48:49], s[48:49], 2, v[58:59]
	v_lshl_add_u64 v[50:51], s[50:51], 2, v[58:59]
	v_lshl_add_u64 v[52:53], s[52:53], 2, v[58:59]
	v_lshl_add_u64 v[54:55], s[54:55], 2, v[58:59]
	v_lshl_add_u64 v[56:57], s[56:57], 2, v[58:59]
	s_lshl_b32 s2, s19, 5
	s_mov_b32 s59, s79
	s_mov_b32 s61, s79
	s_mov_b32 s63, s79
	s_mov_b32 s65, s79
	s_mov_b32 s67, s79
	s_mov_b32 s69, s79
	global_load_dword v42, v[42:43], off nt
	s_nop 0
	global_load_dword v43, v[44:45], off nt
	s_nop 0
	global_load_dword v44, v[46:47], off nt
	global_load_dword v45, v[48:49], off nt
	s_nop 0
	global_load_dword v46, v[50:51], off nt
	global_load_dword v47, v[52:53], off nt
	global_load_dword v48, v[54:55], off nt
	global_load_dword v49, v[56:57], off nt
	v_lshl_add_u64 v[50:51], s[2:3], 2, v[58:59]
	v_lshl_add_u64 v[52:53], s[58:59], 2, v[58:59]
	v_lshl_add_u64 v[54:55], s[60:61], 2, v[58:59]
	v_lshl_add_u64 v[56:57], s[62:63], 2, v[58:59]
	s_waitcnt vmcnt(20)
	v_lshl_add_u64 v[60:61], s[64:65], 2, v[58:59]
	s_waitcnt vmcnt(18)
	v_lshl_add_u64 v[62:63], s[66:67], 2, v[58:59]
	s_waitcnt vmcnt(16)
	v_lshl_add_u64 v[64:65], s[68:69], 2, v[58:59]
	s_mov_b32 s71, s79
	s_mov_b32 s73, s79
	s_mov_b32 s75, s79
	s_mov_b32 s77, s79
	v_lshl_add_u64 v[74:75], s[70:71], 2, v[58:59]
	global_load_dword v50, v[50:51], off nt
	s_nop 0
	global_load_dword v51, v[52:53], off nt
	s_nop 0
	global_load_dword v52, v[54:55], off nt
	global_load_dword v53, v[56:57], off nt
	s_nop 0
	global_load_dword v54, v[60:61], off nt
	global_load_dword v55, v[62:63], off nt
	global_load_dword v56, v[64:65], off nt
	global_load_dword v57, v[74:75], off nt
	v_lshl_add_u64 v[60:61], s[72:73], 2, v[58:59]
	v_lshl_add_u64 v[62:63], s[74:75], 2, v[58:59]
	v_lshl_add_u64 v[64:65], s[76:77], 2, v[58:59]
	s_mov_b32 s83, s79
	s_mov_b32 s87, s79
	s_mov_b32 s89, s79
	s_mov_b32 s91, s79
	s_mov_b32 s93, s79
	v_lshl_add_u64 v[74:75], s[82:83], 2, v[58:59]
	v_lshl_add_u64 v[82:83], s[86:87], 2, v[58:59]
	v_lshl_add_u64 v[84:85], s[88:89], 2, v[58:59]
	v_lshl_add_u64 v[86:87], s[90:91], 2, v[58:59]
	v_lshl_add_u64 v[88:89], s[92:93], 2, v[58:59]
	global_load_dword v58, v[60:61], off nt
	global_load_dword v59, v[62:63], off nt
	s_nop 0
	global_load_dword v60, v[64:65], off nt
	global_load_dword v61, v[74:75], off nt
	global_load_dword v62, v[82:83], off nt
	global_load_dword v63, v[84:85], off nt
	s_nop 0
	global_load_dword v64, v[86:87], off nt
	global_load_dword v65, v[88:89], off nt
	s_mov_b32 s67, 0x800000

; __device__ __forceinline__ unsigned cvt_pk_bf16(float lo, float hi) { unsigned r; asm volatile("v_cvt_pk_bf16_f32 %0, %1, %2" : "=v"(r) : "v"(lo), "v"(hi)); return r; }
; #define LAS __attribute__((address_space(3)))
; __device__ __forceinline__ void titem_finish(const float (&wv)[32], int K, int N, bf16_t* WT, LAS float* scr, int item, int lane, bool upperm, const float* gain) {
;     ...
; #pragma unroll
;     for (int j = 0; j < 4; ++j) { const int n = (lane >> 3) + 8 * j; const LAS float* s = scr + (8 * c) * 33 + n;
;         u32x4 o; o.x = cvt_pk_bf16(s[0 * 33] * g0[0], s[1 * 33] * g0[1]); o.y = cvt_pk_bf16(s[2 * 33] * g0[2], s[3 * 33] * g0[3]); o.z = cvt_pk_bf16(s[4 * 33] * g1[0], s[5 * 33] * g1[1]); o.w = cvt_pk_bf16(s[6 * 33] * g1[2], s[7 * 33] * g1[3]);
;         *(u32x4*)(WT + (size_t)(nd0 + n) * K + k0 + 8 * c) = o; }
;     asm volatile("s_waitcnt lgkmcnt(0)" ::: "memory");
.LBB0_551:
	ds_read2_b32 v[42:43], v77 offset1:33
	v_add_u32_e32 v50, s24, v76
	v_lshl_add_u64 v[46:47], s[16:17], 1, v[74:75]
	v_ashrrev_i32_e32 v53, 31, v50
	v_mad_u64_u32 v[50:51], s[16:17], v50, s101, 0
	s_waitcnt vmcnt(1) lgkmcnt(0)
	v_mul_f32_e32 v42, v38, v42
	v_mul_f32_e32 v43, v39, v43
	v_cvt_pk_bf16_f32 v42, v42, v43
	ds_read2_b32 v[44:45], v77 offset0:66 offset1:99
	v_mov_b32_e32 v52, v51
	v_mad_u64_u32 v[52:53], s[16:17], v53, s101, v[52:53]
	v_mov_b32_e32 v51, v52
	s_waitcnt lgkmcnt(0)
	v_mul_f32_e32 v43, v40, v44
	v_mul_f32_e32 v44, v41, v45
	v_cvt_pk_bf16_f32 v43, v43, v44
	ds_read2_b32 v[44:45], v77 offset0:132 offset1:165
	v_lshl_add_u64 v[50:51], v[50:51], 1, v[46:47]
	s_andn2_b64 vcc, exec, s[12:13]
	s_add_i32 s9, s9, s22
	s_waitcnt vmcnt(0) lgkmcnt(0)
	v_mul_f32_e32 v44, v34, v44
	v_mul_f32_e32 v45, v35, v45
	v_cvt_pk_bf16_f32 v44, v44, v45
	ds_read2_b32 v[48:49], v77 offset0:198 offset1:231
	s_waitcnt lgkmcnt(0)
	v_mul_f32_e32 v45, v36, v48
	v_mul_f32_e32 v48, v37, v49
	v_cvt_pk_bf16_f32 v45, v45, v48
	ds_read2_b32 v[48:49], v77 offset0:8 offset1:41
	global_store_dwordx4 v[50:51], v[42:45], off
	v_add_u32_e32 v50, s24, v78
	v_ashrrev_i32_e32 v53, 31, v50
	v_mad_u64_u32 v[50:51], s[16:17], v50, s101, 0
	s_waitcnt lgkmcnt(0)
	v_mul_f32_e32 v42, v38, v48
	v_mul_f32_e32 v43, v39, v49
	v_cvt_pk_bf16_f32 v42, v42, v43
	ds_read2_b32 v[44:45], v77 offset0:74 offset1:107
	v_mov_b32_e32 v52, v51
	v_mad_u64_u32 v[52:53], s[16:17], v53, s101, v[52:53]
	v_mov_b32_e32 v51, v52
	s_waitcnt lgkmcnt(0)
	v_mul_f32_e32 v43, v40, v44
	v_mul_f32_e32 v44, v41, v45
	v_cvt_pk_bf16_f32 v43, v43, v44
	ds_read2_b32 v[44:45], v77 offset0:140 offset1:173
	v_lshl_add_u64 v[50:51], v[50:51], 1, v[46:47]
	s_waitcnt lgkmcnt(0)
	v_mul_f32_e32 v44, v34, v44
	v_mul_f32_e32 v45, v35, v45
	v_cvt_pk_bf16_f32 v44, v44, v45
	ds_read2_b32 v[48:49], v77 offset0:206 offset1:239
	s_waitcnt lgkmcnt(0)
	v_mul_f32_e32 v45, v36, v48
	v_mul_f32_e32 v48, v37, v49
	v_cvt_pk_bf16_f32 v45, v45, v48
	ds_read2_b32 v[48:49], v77 offset0:16 offset1:49
	global_store_dwordx4 v[50:51], v[42:45], off
	s_waitcnt lgkmcnt(0)
	s_nop 0
	v_mul_f32_e32 v42, v38, v48
	v_mul_f32_e32 v43, v39, v49
	v_cvt_pk_bf16_f32 v42, v42, v43
	ds_read2_b32 v[44:45], v77 offset0:82 offset1:115
	s_waitcnt lgkmcnt(0)
	v_mul_f32_e32 v43, v40, v44
	v_mul_f32_e32 v44, v41, v45
	v_cvt_pk_bf16_f32 v43, v43, v44
	ds_read2_b32 v[44:45], v77 offset0:148 offset1:181
	s_waitcnt lgkmcnt(0)
	v_mul_f32_e32 v44, v34, v44
	v_mul_f32_e32 v45, v35, v45
	v_cvt_pk_bf16_f32 v44, v44, v45
	ds_read2_b32 v[48:49], v77 offset0:214 offset1:247
	v_add_u32_e32 v45, s24, v79
	v_ashrrev_i32_e32 v54, 31, v45
	v_mad_u64_u32 v[50:51], s[16:17], v45, s101, 0
	s_waitcnt lgkmcnt(0)
	v_mul_f32_e32 v45, v36, v48
	v_mul_f32_e32 v48, v37, v49
	v_cvt_pk_bf16_f32 v45, v45, v48
	ds_read2_b32 v[52:53], v77 offset0:24 offset1:57
	v_mov_b32_e32 v48, v51
	v_mad_u64_u32 v[48:49], s[16:17], v54, s101, v[48:49]
	v_mov_b32_e32 v51, v48
	v_lshl_add_u64 v[48:49], v[50:51], 1, v[46:47]
	s_waitcnt lgkmcnt(0)
	v_mul_f32_e32 v38, v38, v52
	global_store_dwordx4 v[48:49], v[42:45], off
	v_mul_f32_e32 v39, v39, v53
	v_cvt_pk_bf16_f32 v38, v38, v39
	ds_read2_b32 v[42:43], v77 offset0:90 offset1:123
	s_waitcnt lgkmcnt(0)
	v_mul_f32_e32 v39, v40, v42
	v_mul_f32_e32 v40, v41, v43
	v_cvt_pk_bf16_f32 v39, v39, v40
	ds_read2_b32 v[40:41], v77 offset0:156 offset1:189
	v_add_u32_e32 v42, s24, v80
	v_ashrrev_i32_e32 v43, 31, v42
	s_waitcnt lgkmcnt(0)
	v_mul_f32_e32 v34, v34, v40
	v_mul_f32_e32 v35, v35, v41
	v_cvt_pk_bf16_f32 v40, v34, v35
	ds_read2_b32 v[34:35], v77 offset0:222 offset1:255
	s_waitcnt lgkmcnt(0)
	v_mul_f32_e32 v34, v36, v34
	v_mul_f32_e32 v35, v37, v35
	v_cvt_pk_bf16_f32 v41, v34, v35
	v_mad_u64_u32 v[34:35], s[16:17], v42, s101, 0
	v_mov_b32_e32 v36, v35
	v_mad_u64_u32 v[36:37], s[16:17], v43, s101, v[36:37]
	v_mov_b32_e32 v35, v36
	v_lshl_add_u64 v[34:35], v[34:35], 1, v[46:47]
	global_store_dwordx4 v[34:35], v[38:41], off
	s_waitcnt lgkmcnt(0)
	s_cbranch_vccz .LBB0_553
	v_mov_b64_e32 v[64:65], v[32:33]
	s_mov_b32 s16, s23
	v_mov_b64_e32 v[62:63], v[30:31]
	v_mov_b64_e32 v[60:61], v[28:29]
	v_mov_b64_e32 v[58:59], v[26:27]
	v_mov_b64_e32 v[56:57], v[24:25]
	v_mov_b64_e32 v[54:55], v[22:23]
	v_mov_b64_e32 v[52:53], v[20:21]
	v_mov_b64_e32 v[50:51], v[18:19]
	v_mov_b64_e32 v[48:49], v[16:17]
	v_mov_b64_e32 v[46:47], v[14:15]
	v_mov_b64_e32 v[44:45], v[12:13]
	v_mov_b64_e32 v[42:43], v[10:11]
	v_mov_b64_e32 v[40:41], v[8:9]
	v_mov_b64_e32 v[38:39], v[6:7]
	v_mov_b64_e32 v[36:37], v[4:5]
	v_mov_b64_e32 v[34:35], v[2:3]
	s_branch .LBB0_544

; __device__ __forceinline__ void convert_phase(CArgs* ap, int l, LAS unsigned char* lds, int gw, int NGW, int wave, int lane) {
;     ...
;                 case 0: W = ap->in[2] + (size_t)l * D * INW; K = D; N = INW; off = O_WIN; break;
;                 case 1: W = ap->in[21] + (size_t)l * 1024 * D; K = 1024; N = D; off = O_WA; break;
;                 case 2: W = ap->in[22] + (size_t)l * 512 * D; K = 512; N = D; off = O_WSG; break;
;                 case 3: W = ap->in[23] + (size_t)l * 512 * D; K = 512; N = D; off = O_WSSM; break;
;                 case 4: W = ap->in[24] + (size_t)l * D * D; K = D; N = D; off = O_WOUT; break;
;                 case 5: W = ap->in[26] + (size_t)l * D * NUP; K = D; N = NUP; off = O_WUP; break;
;                 case 6: W = ap->in[29] + (size_t)l * DFF * D; K = DFF; N = D; off = O_WDN; break;
;                 default: W = ap->in[19] + (size_t)l * 512 * 512; K = 512; N = 512; off = O_WGLU; break;
.LBB0_554:
	v_readlane_b32 s2, v253, 62
	v_readlane_b32 s4, v254, 35
	s_movk_i32 s18, 0x200
	s_mov_b64 s[12:13], 0x2400800
	v_readlane_b32 s3, v253, 63
	v_readlane_b32 s5, v254, 36
	s_movk_i32 s19, 0x800
	s_cbranch_execz .LBB0_531
	s_branch .LBB0_532

; __global__ void __launch_bounds__(NTHR, 2) fwd(Args a) {
	.amdhsa_kernel _ZN2mk3fwdENS_4ArgsE
		.amdhsa_group_segment_fixed_size 0
		.amdhsa_private_segment_fixed_size 0
		.amdhsa_kernarg_size 520
		.amdhsa_user_sgpr_count 2
		.amdhsa_user_sgpr_dispatch_ptr 0
		.amdhsa_user_sgpr_queue_ptr 0
		.amdhsa_user_sgpr_kernarg_segment_ptr 1
		.amdhsa_user_sgpr_dispatch_id 0
		.amdhsa_user_sgpr_kernarg_preload_length 0
		.amdhsa_user_sgpr_kernarg_preload_offset 0
		.amdhsa_user_sgpr_private_segment_size 0
		.amdhsa_uses_dynamic_stack 0
		.amdhsa_enable_private_segment 0
		.amdhsa_system_sgpr_workgroup_id_x 1
		.amdhsa_system_sgpr_workgroup_id_y 0
		.amdhsa_system_sgpr_workgroup_id_z 0
		.amdhsa_system_sgpr_workgroup_info 0
		.amdhsa_system_vgpr_workitem_id 2
		.amdhsa_next_free_vgpr 256
		.amdhsa_next_free_sgpr 102
		.amdhsa_accum_offset 256
		.amdhsa_reserve_vcc 1
		.amdhsa_float_round_mode_32 0
		.amdhsa_float_round_mode_16_64 0
		.amdhsa_float_denorm_mode_32 3
		.amdhsa_float_denorm_mode_16_64 3
		.amdhsa_dx10_clamp 1
		.amdhsa_ieee_mode 1
		.amdhsa_fp16_overflow 0
		.amdhsa_tg_split 0
		.amdhsa_exception_fp_ieee_invalid_op 0
		.amdhsa_exception_fp_denorm_src 0
		.amdhsa_exception_fp_ieee_div_zero 0
		.amdhsa_exception_fp_ieee_overflow 0
		.amdhsa_exception_fp_ieee_underflow 0
		.amdhsa_exception_fp_ieee_inexact 0
		.amdhsa_exception_int_div_zero 0
	.end_amdhsa_kernel

; __global__ void __launch_bounds__(NTHR, 2) fwd(Args a) {
amdhsa.kernels:
  - .agpr_count:     0
    .args:
      - .offset:         0
        .size:           264
        .value_kind:     by_value
      - .offset:         264
        .size:           4
        .value_kind:     hidden_block_count_x
      - .offset:         268
        .size:           4
        .value_kind:     hidden_block_count_y
      - .offset:         272
        .size:           4
        .value_kind:     hidden_block_count_z
      - .offset:         276
        .size:           2
        .value_kind:     hidden_group_size_x
      - .offset:         278
        .size:           2
        .value_kind:     hidden_group_size_y
      - .offset:         280
        .size:           2
        .value_kind:     hidden_group_size_z
      - .offset:         282
        .size:           2
        .value_kind:     hidden_remainder_x
      - .offset:         284
        .size:           2
        .value_kind:     hidden_remainder_y
      - .offset:         286
        .size:           2
        .value_kind:     hidden_remainder_z
      - .offset:         304
        .size:           8
        .value_kind:     hidden_global_offset_x
      - .offset:         312
        .size:           8
        .value_kind:     hidden_global_offset_y
      - .offset:         320
        .size:           8
        .value_kind:     hidden_global_offset_z
      - .offset:         328
        .size:           2
        .value_kind:     hidden_grid_dims
      - .offset:         352
        .size:           8
        .value_kind:     hidden_multigrid_sync_arg
      - .offset:         384
        .size:           4
        .value_kind:     hidden_dynamic_lds_size
    .group_segment_fixed_size: 0
    .kernarg_segment_align: 8
    .kernarg_segment_size: 520
    .language:       OpenCL C
    .language_version:
      - 2
      - 0
    .max_flat_workgroup_size: 512
    .name:           _ZN2mk3fwdENS_4ArgsE
    .private_segment_fixed_size: 0
    .sgpr_count:     108
    .sgpr_spill_count: 291
    .symbol:         _ZN2mk3fwdENS_4ArgsE.kd
    .uniform_work_group_size: 1
    .uses_dynamic_stack: false
    .vgpr_count:     256
    .vgpr_spill_count: 0
    .wavefront_size: 64
